# up_proj epilogue: packed f32 (v_pk_fma/mul/add) for the non-DPP conv tap and the gate arithmetic, 12 fewer VALU issues per 16x16 block
# speedup vs baseline: 1.0191x; 1.0076x over previous
.LBB0_1339:
	v_and_b32_e32 v56, 15, v0
	v_bfe_u32 v57, v0, 4, 2
	s_lshl_b32 s8, s12, 8
	s_add_i32 s8, s8, s63
	s_lshl_b32 s9, s13, 9
	s_lshl_b32 s22, s64, 2
	s_add_i32 s9, s9, s22
	v_lshl_add_u32 v235, v57, 5, s9
	global_load_dwordx4 v[100:103], v235, s[0:1]
	global_load_dwordx4 v[104:107], v235, s[30:31]
	global_load_dwordx4 v[112:115], v235, s[34:35]
	global_load_dwordx4 v[120:123], v235, s[2:3]
	global_load_dwordx4 v[92:95], v235, s[36:37]
	global_load_dwordx4 v[96:99], v235, s[48:49]
	global_load_dwordx4 v[108:111], v235, s[46:47]
	global_load_dwordx4 v[116:119], v235, s[44:45]
	v_cmp_lt_u32_e64 s[10:11], 13, v56
	v_cmp_gt_u32_e64 s[14:15], 2, v56
	v_cmp_eq_u32_e64 s[22:23], 0, v56
	v_lshlrev_b32_e32 v217, 8, v56
	v_lshl_add_u32 v217, v57, 5, v217
	v_add_u32_e32 v217, 0xfffff200, v217
	v_cndmask_b32_e64 v250, 0, 1.0, s[22:23]
	v_cndmask_b32_e64 v251, 0, 1.0, s[14:15]
	v_mul_u32_u24_e32 v234, 0x2c00, v56
	v_lshl_add_u32 v234, v57, 4, v234
	s_mov_b32 s41, 0xbfb8aa3b
	v_mov_b32_e32 v240, 0xbfb8aa3b
	v_mov_b32_e32 v241, 1.0
	s_lshl_b32 s39, s12, 8
	s_add_i32 s39, s39, s63
	s_mul_i32 s39, s39, 0x2c00
	s_lshl_b32 s40, s13, 8
	s_add_i32 s39, s39, s40
	s_lshl_b32 s40, s64, 1
	s_add_i32 s39, s39, s40
	s_add_u32 s16, s70, s39
	s_addc_u32 s17, s71, 0
	s_add_u32 s18, s16, 0x160000
	s_addc_u32 s19, s17, 0
	v_pk_mul_f32 v[192:193], v[192:193], v[242:243] op_sel_hi:[1,0]
	v_pk_mul_f32 v[194:195], v[194:195], v[242:243] op_sel_hi:[1,0]
	v_pk_mul_f32 v[160:161], v[160:161], v[242:243] op_sel_hi:[1,0]
	v_pk_mul_f32 v[162:163], v[162:163], v[242:243] op_sel_hi:[1,0]
	v_pk_mul_f32 v[180:181], v[180:181], v[242:243] op_sel_hi:[1,0]
	v_pk_mul_f32 v[182:183], v[182:183], v[242:243] op_sel_hi:[1,0]
	v_pk_mul_f32 v[156:157], v[156:157], v[242:243] op_sel_hi:[1,0]
	v_pk_mul_f32 v[158:159], v[158:159], v[242:243] op_sel_hi:[1,0]
	v_pk_mul_f32 v[188:189], v[188:189], v[242:243] op_sel:[0,1] op_sel_hi:[1,1]
	v_pk_mul_f32 v[190:191], v[190:191], v[242:243] op_sel:[0,1] op_sel_hi:[1,1]
	v_pk_mul_f32 v[152:153], v[152:153], v[242:243] op_sel:[0,1] op_sel_hi:[1,1]
	v_pk_mul_f32 v[154:155], v[154:155], v[242:243] op_sel:[0,1] op_sel_hi:[1,1]
	v_pk_mul_f32 v[184:185], v[184:185], v[242:243] op_sel:[0,1] op_sel_hi:[1,1]
	v_pk_mul_f32 v[186:187], v[186:187], v[242:243] op_sel:[0,1] op_sel_hi:[1,1]
	v_pk_mul_f32 v[148:149], v[148:149], v[242:243] op_sel:[0,1] op_sel_hi:[1,1]
	v_pk_mul_f32 v[150:151], v[150:151], v[242:243] op_sel:[0,1] op_sel_hi:[1,1]
	v_pk_mul_f32 v[176:177], v[176:177], v[244:245] op_sel_hi:[1,0]
	v_pk_mul_f32 v[178:179], v[178:179], v[244:245] op_sel_hi:[1,0]
	v_pk_mul_f32 v[144:145], v[144:145], v[244:245] op_sel_hi:[1,0]
	v_pk_mul_f32 v[146:147], v[146:147], v[244:245] op_sel_hi:[1,0]
	v_pk_mul_f32 v[172:173], v[172:173], v[244:245] op_sel_hi:[1,0]
	v_pk_mul_f32 v[174:175], v[174:175], v[244:245] op_sel_hi:[1,0]
	v_pk_mul_f32 v[140:141], v[140:141], v[244:245] op_sel_hi:[1,0]
	v_pk_mul_f32 v[142:143], v[142:143], v[244:245] op_sel_hi:[1,0]
	v_pk_mul_f32 v[168:169], v[168:169], v[244:245] op_sel:[0,1] op_sel_hi:[1,1]
	v_pk_mul_f32 v[170:171], v[170:171], v[244:245] op_sel:[0,1] op_sel_hi:[1,1]
	v_pk_mul_f32 v[136:137], v[136:137], v[244:245] op_sel:[0,1] op_sel_hi:[1,1]
	v_pk_mul_f32 v[138:139], v[138:139], v[244:245] op_sel:[0,1] op_sel_hi:[1,1]
	v_pk_mul_f32 v[164:165], v[164:165], v[244:245] op_sel:[0,1] op_sel_hi:[1,1]
	v_pk_mul_f32 v[166:167], v[166:167], v[244:245] op_sel:[0,1] op_sel_hi:[1,1]
	v_pk_mul_f32 v[132:133], v[132:133], v[244:245] op_sel:[0,1] op_sel_hi:[1,1]
	v_pk_mul_f32 v[134:135], v[134:135], v[244:245] op_sel:[0,1] op_sel_hi:[1,1]
	v_pk_mul_f32 v[128:129], v[128:129], v[246:247] op_sel_hi:[1,0]
	v_pk_mul_f32 v[130:131], v[130:131], v[246:247] op_sel_hi:[1,0]
	v_pk_mul_f32 v[64:65], v[64:65], v[246:247] op_sel_hi:[1,0]
	v_pk_mul_f32 v[66:67], v[66:67], v[246:247] op_sel_hi:[1,0]
	v_pk_mul_f32 v[124:125], v[124:125], v[246:247] op_sel_hi:[1,0]
	v_pk_mul_f32 v[126:127], v[126:127], v[246:247] op_sel_hi:[1,0]
	v_pk_mul_f32 v[60:61], v[60:61], v[246:247] op_sel_hi:[1,0]
	v_pk_mul_f32 v[62:63], v[62:63], v[246:247] op_sel_hi:[1,0]
	v_pk_mul_f32 v[88:89], v[88:89], v[246:247] op_sel:[0,1] op_sel_hi:[1,1]
	v_pk_mul_f32 v[90:91], v[90:91], v[246:247] op_sel:[0,1] op_sel_hi:[1,1]
	v_pk_mul_f32 v[24:25], v[24:25], v[246:247] op_sel:[0,1] op_sel_hi:[1,1]
	v_pk_mul_f32 v[26:27], v[26:27], v[246:247] op_sel:[0,1] op_sel_hi:[1,1]
	v_pk_mul_f32 v[84:85], v[84:85], v[246:247] op_sel:[0,1] op_sel_hi:[1,1]
	v_pk_mul_f32 v[86:87], v[86:87], v[246:247] op_sel:[0,1] op_sel_hi:[1,1]
	v_pk_mul_f32 v[20:21], v[20:21], v[246:247] op_sel:[0,1] op_sel_hi:[1,1]
	v_pk_mul_f32 v[22:23], v[22:23], v[246:247] op_sel:[0,1] op_sel_hi:[1,1]
	v_pk_mul_f32 v[80:81], v[80:81], v[248:249] op_sel_hi:[1,0]
	v_pk_mul_f32 v[82:83], v[82:83], v[248:249] op_sel_hi:[1,0]
	v_pk_mul_f32 v[16:17], v[16:17], v[248:249] op_sel_hi:[1,0]
	v_pk_mul_f32 v[18:19], v[18:19], v[248:249] op_sel_hi:[1,0]
	v_pk_mul_f32 v[76:77], v[76:77], v[248:249] op_sel_hi:[1,0]
	v_pk_mul_f32 v[78:79], v[78:79], v[248:249] op_sel_hi:[1,0]
	v_pk_mul_f32 v[12:13], v[12:13], v[248:249] op_sel_hi:[1,0]
	v_pk_mul_f32 v[14:15], v[14:15], v[248:249] op_sel_hi:[1,0]
	v_pk_mul_f32 v[72:73], v[72:73], v[248:249] op_sel:[0,1] op_sel_hi:[1,1]
	v_pk_mul_f32 v[74:75], v[74:75], v[248:249] op_sel:[0,1] op_sel_hi:[1,1]
	v_pk_mul_f32 v[8:9], v[8:9], v[248:249] op_sel:[0,1] op_sel_hi:[1,1]
	v_pk_mul_f32 v[10:11], v[10:11], v[248:249] op_sel:[0,1] op_sel_hi:[1,1]
	v_pk_mul_f32 v[68:69], v[68:69], v[248:249] op_sel:[0,1] op_sel_hi:[1,1]
	v_pk_mul_f32 v[70:71], v[70:71], v[248:249] op_sel:[0,1] op_sel_hi:[1,1]
	v_pk_mul_f32 v[4:5], v[4:5], v[248:249] op_sel:[0,1] op_sel_hi:[1,1]
	v_pk_mul_f32 v[6:7], v[6:7], v[248:249] op_sel:[0,1] op_sel_hi:[1,1]
	v_add_u32_e32 v58, s78, v217
	s_and_saveexec_b64 s[8:9], s[10:11]
	ds_write_b128 v58, v[168:171]
	ds_write_b128 v58, v[136:139] offset:16
	ds_write_b128 v58, v[164:167] offset:128
	ds_write_b128 v58, v[132:135] offset:144
	ds_write_b128 v58, v[72:75] offset:4096
	ds_write_b128 v58, v[8:11] offset:4112
	ds_write_b128 v58, v[68:71] offset:4224
	ds_write_b128 v58, v[4:7] offset:4240
	s_mov_b64 exec, s[8:9]
	s_waitcnt lgkmcnt(0)
	s_barrier
	s_waitcnt vmcnt(0)
	v_mul_f32_e32 v28, v104, v250
	v_mul_f32_e32 v29, v105, v250
	v_mul_f32_e32 v30, v106, v250
	v_mul_f32_e32 v31, v107, v250
	v_mul_f32_e32 v32, v100, v251
	v_mul_f32_e32 v33, v101, v251
	v_mul_f32_e32 v34, v102, v251
	v_mul_f32_e32 v35, v103, v251
	v_mul_f32_e32 v36, v96, v250
	v_mul_f32_e32 v37, v97, v250
	v_mul_f32_e32 v38, v98, v250
	v_mul_f32_e32 v39, v99, v250
	v_mul_f32_e32 v40, v92, v251
	v_mul_f32_e32 v41, v93, v251
	v_mul_f32_e32 v42, v94, v251
	v_mul_f32_e32 v43, v95, v251
	v_mov_b32_e32 v196, 0
	v_mov_b32_e32 v197, 0
	v_mov_b32_e32 v198, 0
	v_mov_b32_e32 v199, 0
	v_mov_b32_e32 v200, 0
	v_mov_b32_e32 v201, 0
	v_mov_b32_e32 v202, 0
	v_mov_b32_e32 v203, 0
	v_mov_b32_e32 v204, 0
	v_mov_b32_e32 v205, 0
	v_mov_b32_e32 v206, 0
	v_mov_b32_e32 v207, 0
	v_mov_b32_e32 v208, 0
	v_mov_b32_e32 v209, 0
	v_mov_b32_e32 v210, 0
	v_mov_b32_e32 v211, 0
	s_cmp_eq_u32 s63, 0
	s_cbranch_scc1 .Leu_pv0_skip_n0
	v_add_u32_e32 v58, s67, v217
	s_and_saveexec_b64 s[8:9], s[10:11]
	ds_read_b128 v[196:199], v58 offset:0
	ds_read_b128 v[200:203], v58 offset:128
	s_mov_b64 exec, s[8:9]
.Leu_pv0_skip_n0:
	s_cmp_eq_u32 s63, 0
	s_movk_i32 s40, 0x1000
	s_cselect_b32 s39, 0x800, s40
	s_add_i32 s39, s39, s67
	v_add_u32_e32 v59, s39, v217
	s_and_saveexec_b64 s[8:9], s[10:11]
	ds_read_b128 v[204:207], v59 offset:0
	ds_read_b128 v[208:211], v59 offset:128
	s_mov_b64 exec, s[8:9]
	s_waitcnt lgkmcnt(0)
	v_pk_fma_f32 v[44:45], v[112:113], v[192:193], v[120:121]
	v_pk_fma_f32 v[46:47], v[114:115], v[194:195], v[122:123]
	v_pk_fma_f32 v[48:49], v[108:109], v[180:181], v[116:117]
	v_pk_fma_f32 v[50:51], v[110:111], v[182:183], v[118:119]
	v_fmac_f32_dpp v44, v192, v104 row_shr:1 row_mask:0xf bank_mask:0xf
	v_fmac_f32_dpp v45, v193, v105 row_shr:1 row_mask:0xf bank_mask:0xf
	v_fmac_f32_dpp v46, v194, v106 row_shr:1 row_mask:0xf bank_mask:0xf
	v_fmac_f32_dpp v47, v195, v107 row_shr:1 row_mask:0xf bank_mask:0xf
	v_fmac_f32_dpp v48, v180, v96 row_shr:1 row_mask:0xf bank_mask:0xf
	v_fmac_f32_dpp v49, v181, v97 row_shr:1 row_mask:0xf bank_mask:0xf
	v_fmac_f32_dpp v50, v182, v98 row_shr:1 row_mask:0xf bank_mask:0xf
	v_fmac_f32_dpp v51, v183, v99 row_shr:1 row_mask:0xf bank_mask:0xf
	v_fmac_f32_dpp v44, v192, v100 row_shr:2 row_mask:0xf bank_mask:0xf
	v_fmac_f32_dpp v45, v193, v101 row_shr:2 row_mask:0xf bank_mask:0xf
	v_fmac_f32_dpp v46, v194, v102 row_shr:2 row_mask:0xf bank_mask:0xf
	v_fmac_f32_dpp v47, v195, v103 row_shr:2 row_mask:0xf bank_mask:0xf
	v_fmac_f32_dpp v48, v180, v92 row_shr:2 row_mask:0xf bank_mask:0xf
	v_fmac_f32_dpp v49, v181, v93 row_shr:2 row_mask:0xf bank_mask:0xf
	v_fmac_f32_dpp v50, v182, v94 row_shr:2 row_mask:0xf bank_mask:0xf
	v_fmac_f32_dpp v51, v183, v95 row_shr:2 row_mask:0xf bank_mask:0xf
	v_fmac_f32_dpp v44, v196, v28 row_ror:1 row_mask:0xf bank_mask:0xf
	v_fmac_f32_dpp v45, v197, v29 row_ror:1 row_mask:0xf bank_mask:0xf
	v_fmac_f32_dpp v46, v198, v30 row_ror:1 row_mask:0xf bank_mask:0xf
	v_fmac_f32_dpp v47, v199, v31 row_ror:1 row_mask:0xf bank_mask:0xf
	v_fmac_f32_dpp v48, v200, v36 row_ror:1 row_mask:0xf bank_mask:0xf
	v_fmac_f32_dpp v49, v201, v37 row_ror:1 row_mask:0xf bank_mask:0xf
	v_fmac_f32_dpp v50, v202, v38 row_ror:1 row_mask:0xf bank_mask:0xf
	v_fmac_f32_dpp v51, v203, v39 row_ror:1 row_mask:0xf bank_mask:0xf
	v_fmac_f32_dpp v44, v196, v32 row_ror:2 row_mask:0xf bank_mask:0xf
	v_fmac_f32_dpp v45, v197, v33 row_ror:2 row_mask:0xf bank_mask:0xf
	v_fmac_f32_dpp v46, v198, v34 row_ror:2 row_mask:0xf bank_mask:0xf
	v_fmac_f32_dpp v47, v199, v35 row_ror:2 row_mask:0xf bank_mask:0xf
	v_fmac_f32_dpp v48, v200, v40 row_ror:2 row_mask:0xf bank_mask:0xf
	v_fmac_f32_dpp v49, v201, v41 row_ror:2 row_mask:0xf bank_mask:0xf
	v_fmac_f32_dpp v50, v202, v42 row_ror:2 row_mask:0xf bank_mask:0xf
	v_fmac_f32_dpp v51, v203, v43 row_ror:2 row_mask:0xf bank_mask:0xf
	v_pk_mul_f32 v[52:53], v[44:45], v[240:241] op_sel_hi:[1,0]
	v_pk_mul_f32 v[54:55], v[46:47], v[240:241] op_sel_hi:[1,0]
	v_exp_f32_e32 v52, v52
	v_exp_f32_e32 v53, v53
	v_exp_f32_e32 v54, v54
	v_exp_f32_e32 v55, v55
	v_pk_add_f32 v[52:53], v[52:53], v[240:241] op_sel:[0,1] op_sel_hi:[1,1]
	v_pk_add_f32 v[54:55], v[54:55], v[240:241] op_sel:[0,1] op_sel_hi:[1,1]
	v_rcp_f32_e32 v52, v52
	v_rcp_f32_e32 v53, v53
	v_rcp_f32_e32 v54, v54
	v_rcp_f32_e32 v55, v55
	v_pk_mul_f32 v[44:45], v[44:45], v[52:53]
	v_pk_mul_f32 v[46:47], v[46:47], v[54:55]
	v_pk_mul_f32 v[44:45], v[48:49], v[44:45]
	v_pk_mul_f32 v[46:47], v[50:51], v[46:47]
	v_cvt_pk_bf16_f32 v242, v44, v45
	v_cvt_pk_bf16_f32 v243, v46, v47
	s_cmp_lg_u32 s63, 0
	s_cbranch_scc1 .Leu_halo_skip_a0n0
	v_mul_u32_u24_e32 v58, 0xb000, v56
	v_lshl_add_u32 v58, v57, 5, v58
	s_mul_i32 s39, s12, 0x2c000
	s_lshl_b32 s40, s13, 9
	s_add_i32 s39, s39, s40
	s_lshl_b32 s40, s64, 2
	s_add_i32 s39, s39, s40
	s_add_u32 s20, s72, s39
	s_addc_u32 s21, s73, 0
	s_add_u32 s22, s20, 0x5800
	s_addc_u32 s23, s21, 0
	s_and_saveexec_b64 s[8:9], s[14:15]
	global_store_dwordx4 v58, v[192:195], s[20:21]
	global_store_dwordx4 v58, v[180:183], s[22:23]
	s_mov_b64 exec, s[8:9]
.Leu_halo_skip_a0n0:
	v_pk_fma_f32 v[44:45], v[112:113], v[188:189], v[120:121]
	v_pk_fma_f32 v[46:47], v[114:115], v[190:191], v[122:123]
	v_pk_fma_f32 v[48:49], v[108:109], v[184:185], v[116:117]
	v_pk_fma_f32 v[50:51], v[110:111], v[186:187], v[118:119]
	v_fmac_f32_dpp v44, v188, v104 row_shr:1 row_mask:0xf bank_mask:0xf
	v_fmac_f32_dpp v45, v189, v105 row_shr:1 row_mask:0xf bank_mask:0xf
	v_fmac_f32_dpp v46, v190, v106 row_shr:1 row_mask:0xf bank_mask:0xf
	v_fmac_f32_dpp v47, v191, v107 row_shr:1 row_mask:0xf bank_mask:0xf
	v_fmac_f32_dpp v48, v184, v96 row_shr:1 row_mask:0xf bank_mask:0xf
	v_fmac_f32_dpp v49, v185, v97 row_shr:1 row_mask:0xf bank_mask:0xf
	v_fmac_f32_dpp v50, v186, v98 row_shr:1 row_mask:0xf bank_mask:0xf
	v_fmac_f32_dpp v51, v187, v99 row_shr:1 row_mask:0xf bank_mask:0xf
	v_fmac_f32_dpp v44, v188, v100 row_shr:2 row_mask:0xf bank_mask:0xf
	v_fmac_f32_dpp v45, v189, v101 row_shr:2 row_mask:0xf bank_mask:0xf
	v_fmac_f32_dpp v46, v190, v102 row_shr:2 row_mask:0xf bank_mask:0xf
	v_fmac_f32_dpp v47, v191, v103 row_shr:2 row_mask:0xf bank_mask:0xf
	v_fmac_f32_dpp v48, v184, v92 row_shr:2 row_mask:0xf bank_mask:0xf
	v_fmac_f32_dpp v49, v185, v93 row_shr:2 row_mask:0xf bank_mask:0xf
	v_fmac_f32_dpp v50, v186, v94 row_shr:2 row_mask:0xf bank_mask:0xf
	v_fmac_f32_dpp v51, v187, v95 row_shr:2 row_mask:0xf bank_mask:0xf
	v_fmac_f32_dpp v44, v192, v28 row_ror:1 row_mask:0xf bank_mask:0xf
	v_fmac_f32_dpp v45, v193, v29 row_ror:1 row_mask:0xf bank_mask:0xf
	v_fmac_f32_dpp v46, v194, v30 row_ror:1 row_mask:0xf bank_mask:0xf
	v_fmac_f32_dpp v47, v195, v31 row_ror:1 row_mask:0xf bank_mask:0xf
	v_fmac_f32_dpp v48, v180, v36 row_ror:1 row_mask:0xf bank_mask:0xf
	v_fmac_f32_dpp v49, v181, v37 row_ror:1 row_mask:0xf bank_mask:0xf
	v_fmac_f32_dpp v50, v182, v38 row_ror:1 row_mask:0xf bank_mask:0xf
	v_fmac_f32_dpp v51, v183, v39 row_ror:1 row_mask:0xf bank_mask:0xf
	v_fmac_f32_dpp v44, v192, v32 row_ror:2 row_mask:0xf bank_mask:0xf
	v_fmac_f32_dpp v45, v193, v33 row_ror:2 row_mask:0xf bank_mask:0xf
	v_fmac_f32_dpp v46, v194, v34 row_ror:2 row_mask:0xf bank_mask:0xf
	v_fmac_f32_dpp v47, v195, v35 row_ror:2 row_mask:0xf bank_mask:0xf
	v_fmac_f32_dpp v48, v180, v40 row_ror:2 row_mask:0xf bank_mask:0xf
	v_fmac_f32_dpp v49, v181, v41 row_ror:2 row_mask:0xf bank_mask:0xf
	v_fmac_f32_dpp v50, v182, v42 row_ror:2 row_mask:0xf bank_mask:0xf
	v_fmac_f32_dpp v51, v183, v43 row_ror:2 row_mask:0xf bank_mask:0xf
	v_pk_mul_f32 v[52:53], v[44:45], v[240:241] op_sel_hi:[1,0]
	v_pk_mul_f32 v[54:55], v[46:47], v[240:241] op_sel_hi:[1,0]
	v_exp_f32_e32 v52, v52
	v_exp_f32_e32 v53, v53
	v_exp_f32_e32 v54, v54
	v_exp_f32_e32 v55, v55
	v_pk_add_f32 v[52:53], v[52:53], v[240:241] op_sel:[0,1] op_sel_hi:[1,1]
	v_pk_add_f32 v[54:55], v[54:55], v[240:241] op_sel:[0,1] op_sel_hi:[1,1]
	v_rcp_f32_e32 v52, v52
	v_rcp_f32_e32 v53, v53
	v_rcp_f32_e32 v54, v54
	v_rcp_f32_e32 v55, v55
	v_pk_mul_f32 v[44:45], v[44:45], v[52:53]
	v_pk_mul_f32 v[46:47], v[46:47], v[54:55]
	v_pk_mul_f32 v[44:45], v[48:49], v[44:45]
	v_pk_mul_f32 v[46:47], v[50:51], v[46:47]
	v_cvt_pk_bf16_f32 v244, v44, v45
	v_cvt_pk_bf16_f32 v245, v46, v47
	v_pk_fma_f32 v[44:45], v[112:113], v[176:177], v[120:121]
	v_pk_fma_f32 v[46:47], v[114:115], v[178:179], v[122:123]
	v_pk_fma_f32 v[48:49], v[108:109], v[172:173], v[116:117]
	v_pk_fma_f32 v[50:51], v[110:111], v[174:175], v[118:119]
	v_fmac_f32_dpp v44, v176, v104 row_shr:1 row_mask:0xf bank_mask:0xf
	v_fmac_f32_dpp v45, v177, v105 row_shr:1 row_mask:0xf bank_mask:0xf
	v_fmac_f32_dpp v46, v178, v106 row_shr:1 row_mask:0xf bank_mask:0xf
	v_fmac_f32_dpp v47, v179, v107 row_shr:1 row_mask:0xf bank_mask:0xf
	v_fmac_f32_dpp v48, v172, v96 row_shr:1 row_mask:0xf bank_mask:0xf
	v_fmac_f32_dpp v49, v173, v97 row_shr:1 row_mask:0xf bank_mask:0xf
	v_fmac_f32_dpp v50, v174, v98 row_shr:1 row_mask:0xf bank_mask:0xf
	v_fmac_f32_dpp v51, v175, v99 row_shr:1 row_mask:0xf bank_mask:0xf
	v_fmac_f32_dpp v44, v176, v100 row_shr:2 row_mask:0xf bank_mask:0xf
	v_fmac_f32_dpp v45, v177, v101 row_shr:2 row_mask:0xf bank_mask:0xf
	v_fmac_f32_dpp v46, v178, v102 row_shr:2 row_mask:0xf bank_mask:0xf
	v_fmac_f32_dpp v47, v179, v103 row_shr:2 row_mask:0xf bank_mask:0xf
	v_fmac_f32_dpp v48, v172, v92 row_shr:2 row_mask:0xf bank_mask:0xf
	v_fmac_f32_dpp v49, v173, v93 row_shr:2 row_mask:0xf bank_mask:0xf
	v_fmac_f32_dpp v50, v174, v94 row_shr:2 row_mask:0xf bank_mask:0xf
	v_fmac_f32_dpp v51, v175, v95 row_shr:2 row_mask:0xf bank_mask:0xf
	v_fmac_f32_dpp v44, v188, v28 row_ror:1 row_mask:0xf bank_mask:0xf
	v_fmac_f32_dpp v45, v189, v29 row_ror:1 row_mask:0xf bank_mask:0xf
	v_fmac_f32_dpp v46, v190, v30 row_ror:1 row_mask:0xf bank_mask:0xf
	v_fmac_f32_dpp v47, v191, v31 row_ror:1 row_mask:0xf bank_mask:0xf
	v_fmac_f32_dpp v48, v184, v36 row_ror:1 row_mask:0xf bank_mask:0xf
	v_fmac_f32_dpp v49, v185, v37 row_ror:1 row_mask:0xf bank_mask:0xf
	v_fmac_f32_dpp v50, v186, v38 row_ror:1 row_mask:0xf bank_mask:0xf
	v_fmac_f32_dpp v51, v187, v39 row_ror:1 row_mask:0xf bank_mask:0xf
	v_fmac_f32_dpp v44, v188, v32 row_ror:2 row_mask:0xf bank_mask:0xf
	v_fmac_f32_dpp v45, v189, v33 row_ror:2 row_mask:0xf bank_mask:0xf
	v_fmac_f32_dpp v46, v190, v34 row_ror:2 row_mask:0xf bank_mask:0xf
	v_fmac_f32_dpp v47, v191, v35 row_ror:2 row_mask:0xf bank_mask:0xf
	v_fmac_f32_dpp v48, v184, v40 row_ror:2 row_mask:0xf bank_mask:0xf
	v_fmac_f32_dpp v49, v185, v41 row_ror:2 row_mask:0xf bank_mask:0xf
	v_fmac_f32_dpp v50, v186, v42 row_ror:2 row_mask:0xf bank_mask:0xf
	v_fmac_f32_dpp v51, v187, v43 row_ror:2 row_mask:0xf bank_mask:0xf
	v_pk_mul_f32 v[52:53], v[44:45], v[240:241] op_sel_hi:[1,0]
	v_pk_mul_f32 v[54:55], v[46:47], v[240:241] op_sel_hi:[1,0]
	v_exp_f32_e32 v52, v52
	v_exp_f32_e32 v53, v53
	v_exp_f32_e32 v54, v54
	v_exp_f32_e32 v55, v55
	v_pk_add_f32 v[52:53], v[52:53], v[240:241] op_sel:[0,1] op_sel_hi:[1,1]
	v_pk_add_f32 v[54:55], v[54:55], v[240:241] op_sel:[0,1] op_sel_hi:[1,1]
	v_rcp_f32_e32 v52, v52
	v_rcp_f32_e32 v53, v53
	v_rcp_f32_e32 v54, v54
	v_rcp_f32_e32 v55, v55
	v_pk_mul_f32 v[44:45], v[44:45], v[52:53]
	v_pk_mul_f32 v[46:47], v[46:47], v[54:55]
	v_pk_mul_f32 v[44:45], v[48:49], v[44:45]
	v_pk_mul_f32 v[46:47], v[50:51], v[46:47]
	v_cvt_pk_bf16_f32 v246, v44, v45
	v_cvt_pk_bf16_f32 v247, v46, v47
	v_pk_fma_f32 v[44:45], v[112:113], v[168:169], v[120:121]
	v_pk_fma_f32 v[46:47], v[114:115], v[170:171], v[122:123]
	v_pk_fma_f32 v[48:49], v[108:109], v[164:165], v[116:117]
	v_pk_fma_f32 v[50:51], v[110:111], v[166:167], v[118:119]
	v_fmac_f32_dpp v44, v168, v104 row_shr:1 row_mask:0xf bank_mask:0xf
	v_fmac_f32_dpp v45, v169, v105 row_shr:1 row_mask:0xf bank_mask:0xf
	v_fmac_f32_dpp v46, v170, v106 row_shr:1 row_mask:0xf bank_mask:0xf
	v_fmac_f32_dpp v47, v171, v107 row_shr:1 row_mask:0xf bank_mask:0xf
	v_fmac_f32_dpp v48, v164, v96 row_shr:1 row_mask:0xf bank_mask:0xf
	v_fmac_f32_dpp v49, v165, v97 row_shr:1 row_mask:0xf bank_mask:0xf
	v_fmac_f32_dpp v50, v166, v98 row_shr:1 row_mask:0xf bank_mask:0xf
	v_fmac_f32_dpp v51, v167, v99 row_shr:1 row_mask:0xf bank_mask:0xf
	v_fmac_f32_dpp v44, v168, v100 row_shr:2 row_mask:0xf bank_mask:0xf
	v_fmac_f32_dpp v45, v169, v101 row_shr:2 row_mask:0xf bank_mask:0xf
	v_fmac_f32_dpp v46, v170, v102 row_shr:2 row_mask:0xf bank_mask:0xf
	v_fmac_f32_dpp v47, v171, v103 row_shr:2 row_mask:0xf bank_mask:0xf
	v_fmac_f32_dpp v48, v164, v92 row_shr:2 row_mask:0xf bank_mask:0xf
	v_fmac_f32_dpp v49, v165, v93 row_shr:2 row_mask:0xf bank_mask:0xf
	v_fmac_f32_dpp v50, v166, v94 row_shr:2 row_mask:0xf bank_mask:0xf
	v_fmac_f32_dpp v51, v167, v95 row_shr:2 row_mask:0xf bank_mask:0xf
	v_fmac_f32_dpp v44, v176, v28 row_ror:1 row_mask:0xf bank_mask:0xf
	v_fmac_f32_dpp v45, v177, v29 row_ror:1 row_mask:0xf bank_mask:0xf
	v_fmac_f32_dpp v46, v178, v30 row_ror:1 row_mask:0xf bank_mask:0xf
	v_fmac_f32_dpp v47, v179, v31 row_ror:1 row_mask:0xf bank_mask:0xf
	v_fmac_f32_dpp v48, v172, v36 row_ror:1 row_mask:0xf bank_mask:0xf
	v_fmac_f32_dpp v49, v173, v37 row_ror:1 row_mask:0xf bank_mask:0xf
	v_fmac_f32_dpp v50, v174, v38 row_ror:1 row_mask:0xf bank_mask:0xf
	v_fmac_f32_dpp v51, v175, v39 row_ror:1 row_mask:0xf bank_mask:0xf
	v_fmac_f32_dpp v44, v176, v32 row_ror:2 row_mask:0xf bank_mask:0xf
	v_fmac_f32_dpp v45, v177, v33 row_ror:2 row_mask:0xf bank_mask:0xf
	v_fmac_f32_dpp v46, v178, v34 row_ror:2 row_mask:0xf bank_mask:0xf
	v_fmac_f32_dpp v47, v179, v35 row_ror:2 row_mask:0xf bank_mask:0xf
	v_fmac_f32_dpp v48, v172, v40 row_ror:2 row_mask:0xf bank_mask:0xf
	v_fmac_f32_dpp v49, v173, v41 row_ror:2 row_mask:0xf bank_mask:0xf
	v_fmac_f32_dpp v50, v174, v42 row_ror:2 row_mask:0xf bank_mask:0xf
	v_fmac_f32_dpp v51, v175, v43 row_ror:2 row_mask:0xf bank_mask:0xf
	v_pk_mul_f32 v[52:53], v[44:45], v[240:241] op_sel_hi:[1,0]
	v_pk_mul_f32 v[54:55], v[46:47], v[240:241] op_sel_hi:[1,0]
	v_exp_f32_e32 v52, v52
	v_exp_f32_e32 v53, v53
	v_exp_f32_e32 v54, v54
	v_exp_f32_e32 v55, v55
	v_pk_add_f32 v[52:53], v[52:53], v[240:241] op_sel:[0,1] op_sel_hi:[1,1]
	v_pk_add_f32 v[54:55], v[54:55], v[240:241] op_sel:[0,1] op_sel_hi:[1,1]
	v_rcp_f32_e32 v52, v52
	v_rcp_f32_e32 v53, v53
	v_rcp_f32_e32 v54, v54
	v_rcp_f32_e32 v55, v55
	v_pk_mul_f32 v[44:45], v[44:45], v[52:53]
	v_pk_mul_f32 v[46:47], v[46:47], v[54:55]
	v_pk_mul_f32 v[44:45], v[48:49], v[44:45]
	v_pk_mul_f32 v[46:47], v[50:51], v[46:47]
	v_cvt_pk_bf16_f32 v248, v44, v45
	v_cvt_pk_bf16_f32 v249, v46, v47
	global_load_dwordx4 v[236:239], v235, s[0:1] offset:16
	global_load_dwordx4 v[192:195], v235, s[30:31] offset:16
	global_load_dwordx4 v[180:183], v235, s[34:35] offset:16
	global_load_dwordx4 v[188:191], v235, s[2:3] offset:16
	global_load_dwordx4 v[184:187], v235, s[36:37] offset:16
	global_load_dwordx4 v[176:179], v235, s[48:49] offset:16
	global_load_dwordx4 v[172:175], v235, s[46:47] offset:16
	global_load_dwordx4 v[168:171], v235, s[44:45] offset:16
	v_pk_fma_f32 v[44:45], v[112:113], v[128:129], v[120:121]
	v_pk_fma_f32 v[46:47], v[114:115], v[130:131], v[122:123]
	v_pk_fma_f32 v[48:49], v[108:109], v[124:125], v[116:117]
	v_pk_fma_f32 v[50:51], v[110:111], v[126:127], v[118:119]
	v_fmac_f32_dpp v44, v128, v104 row_shr:1 row_mask:0xf bank_mask:0xf
	v_fmac_f32_dpp v45, v129, v105 row_shr:1 row_mask:0xf bank_mask:0xf
	v_fmac_f32_dpp v46, v130, v106 row_shr:1 row_mask:0xf bank_mask:0xf
	v_fmac_f32_dpp v47, v131, v107 row_shr:1 row_mask:0xf bank_mask:0xf
	v_fmac_f32_dpp v48, v124, v96 row_shr:1 row_mask:0xf bank_mask:0xf
	v_fmac_f32_dpp v49, v125, v97 row_shr:1 row_mask:0xf bank_mask:0xf
	v_fmac_f32_dpp v50, v126, v98 row_shr:1 row_mask:0xf bank_mask:0xf
	v_fmac_f32_dpp v51, v127, v99 row_shr:1 row_mask:0xf bank_mask:0xf
	v_fmac_f32_dpp v44, v128, v100 row_shr:2 row_mask:0xf bank_mask:0xf
	v_fmac_f32_dpp v45, v129, v101 row_shr:2 row_mask:0xf bank_mask:0xf
	v_fmac_f32_dpp v46, v130, v102 row_shr:2 row_mask:0xf bank_mask:0xf
	v_fmac_f32_dpp v47, v131, v103 row_shr:2 row_mask:0xf bank_mask:0xf
	v_fmac_f32_dpp v48, v124, v92 row_shr:2 row_mask:0xf bank_mask:0xf
	v_fmac_f32_dpp v49, v125, v93 row_shr:2 row_mask:0xf bank_mask:0xf
	v_fmac_f32_dpp v50, v126, v94 row_shr:2 row_mask:0xf bank_mask:0xf
	v_fmac_f32_dpp v51, v127, v95 row_shr:2 row_mask:0xf bank_mask:0xf
	v_fmac_f32_dpp v44, v204, v28 row_ror:1 row_mask:0xf bank_mask:0xf
	v_fmac_f32_dpp v45, v205, v29 row_ror:1 row_mask:0xf bank_mask:0xf
	v_fmac_f32_dpp v46, v206, v30 row_ror:1 row_mask:0xf bank_mask:0xf
	v_fmac_f32_dpp v47, v207, v31 row_ror:1 row_mask:0xf bank_mask:0xf
	v_fmac_f32_dpp v48, v208, v36 row_ror:1 row_mask:0xf bank_mask:0xf
	v_fmac_f32_dpp v49, v209, v37 row_ror:1 row_mask:0xf bank_mask:0xf
	v_fmac_f32_dpp v50, v210, v38 row_ror:1 row_mask:0xf bank_mask:0xf
	v_fmac_f32_dpp v51, v211, v39 row_ror:1 row_mask:0xf bank_mask:0xf
	v_fmac_f32_dpp v44, v204, v32 row_ror:2 row_mask:0xf bank_mask:0xf
	v_fmac_f32_dpp v45, v205, v33 row_ror:2 row_mask:0xf bank_mask:0xf
	v_fmac_f32_dpp v46, v206, v34 row_ror:2 row_mask:0xf bank_mask:0xf
	v_fmac_f32_dpp v47, v207, v35 row_ror:2 row_mask:0xf bank_mask:0xf
	v_fmac_f32_dpp v48, v208, v40 row_ror:2 row_mask:0xf bank_mask:0xf
	v_fmac_f32_dpp v49, v209, v41 row_ror:2 row_mask:0xf bank_mask:0xf
	v_fmac_f32_dpp v50, v210, v42 row_ror:2 row_mask:0xf bank_mask:0xf
	v_fmac_f32_dpp v51, v211, v43 row_ror:2 row_mask:0xf bank_mask:0xf
	v_pk_mul_f32 v[52:53], v[44:45], v[240:241] op_sel_hi:[1,0]
	v_pk_mul_f32 v[54:55], v[46:47], v[240:241] op_sel_hi:[1,0]
	v_exp_f32_e32 v52, v52
	v_exp_f32_e32 v53, v53
	v_exp_f32_e32 v54, v54
	v_exp_f32_e32 v55, v55
	v_pk_add_f32 v[52:53], v[52:53], v[240:241] op_sel:[0,1] op_sel_hi:[1,1]
	v_pk_add_f32 v[54:55], v[54:55], v[240:241] op_sel:[0,1] op_sel_hi:[1,1]
	v_rcp_f32_e32 v52, v52
	v_rcp_f32_e32 v53, v53
	v_rcp_f32_e32 v54, v54
	v_rcp_f32_e32 v55, v55
	v_pk_mul_f32 v[44:45], v[44:45], v[52:53]
	v_pk_mul_f32 v[46:47], v[46:47], v[54:55]
	v_pk_mul_f32 v[44:45], v[48:49], v[44:45]
	v_pk_mul_f32 v[46:47], v[50:51], v[46:47]
	v_cvt_pk_bf16_f32 v164, v44, v45
	v_cvt_pk_bf16_f32 v165, v46, v47
	v_pk_fma_f32 v[44:45], v[112:113], v[88:89], v[120:121]
	v_pk_fma_f32 v[46:47], v[114:115], v[90:91], v[122:123]
	v_pk_fma_f32 v[48:49], v[108:109], v[84:85], v[116:117]
	v_pk_fma_f32 v[50:51], v[110:111], v[86:87], v[118:119]
	v_fmac_f32_dpp v44, v88, v104 row_shr:1 row_mask:0xf bank_mask:0xf
	v_fmac_f32_dpp v45, v89, v105 row_shr:1 row_mask:0xf bank_mask:0xf
	v_fmac_f32_dpp v46, v90, v106 row_shr:1 row_mask:0xf bank_mask:0xf
	v_fmac_f32_dpp v47, v91, v107 row_shr:1 row_mask:0xf bank_mask:0xf
	v_fmac_f32_dpp v48, v84, v96 row_shr:1 row_mask:0xf bank_mask:0xf
	v_fmac_f32_dpp v49, v85, v97 row_shr:1 row_mask:0xf bank_mask:0xf
	v_fmac_f32_dpp v50, v86, v98 row_shr:1 row_mask:0xf bank_mask:0xf
	v_fmac_f32_dpp v51, v87, v99 row_shr:1 row_mask:0xf bank_mask:0xf
	v_fmac_f32_dpp v44, v88, v100 row_shr:2 row_mask:0xf bank_mask:0xf
	v_fmac_f32_dpp v45, v89, v101 row_shr:2 row_mask:0xf bank_mask:0xf
	v_fmac_f32_dpp v46, v90, v102 row_shr:2 row_mask:0xf bank_mask:0xf
	v_fmac_f32_dpp v47, v91, v103 row_shr:2 row_mask:0xf bank_mask:0xf
	v_fmac_f32_dpp v48, v84, v92 row_shr:2 row_mask:0xf bank_mask:0xf
	v_fmac_f32_dpp v49, v85, v93 row_shr:2 row_mask:0xf bank_mask:0xf
	v_fmac_f32_dpp v50, v86, v94 row_shr:2 row_mask:0xf bank_mask:0xf
	v_fmac_f32_dpp v51, v87, v95 row_shr:2 row_mask:0xf bank_mask:0xf
	v_fmac_f32_dpp v44, v128, v28 row_ror:1 row_mask:0xf bank_mask:0xf
	v_fmac_f32_dpp v45, v129, v29 row_ror:1 row_mask:0xf bank_mask:0xf
	v_fmac_f32_dpp v46, v130, v30 row_ror:1 row_mask:0xf bank_mask:0xf
	v_fmac_f32_dpp v47, v131, v31 row_ror:1 row_mask:0xf bank_mask:0xf
	v_fmac_f32_dpp v48, v124, v36 row_ror:1 row_mask:0xf bank_mask:0xf
	v_fmac_f32_dpp v49, v125, v37 row_ror:1 row_mask:0xf bank_mask:0xf
	v_fmac_f32_dpp v50, v126, v38 row_ror:1 row_mask:0xf bank_mask:0xf
	v_fmac_f32_dpp v51, v127, v39 row_ror:1 row_mask:0xf bank_mask:0xf
	v_fmac_f32_dpp v44, v128, v32 row_ror:2 row_mask:0xf bank_mask:0xf
	v_fmac_f32_dpp v45, v129, v33 row_ror:2 row_mask:0xf bank_mask:0xf
	v_fmac_f32_dpp v46, v130, v34 row_ror:2 row_mask:0xf bank_mask:0xf
	v_fmac_f32_dpp v47, v131, v35 row_ror:2 row_mask:0xf bank_mask:0xf
	v_fmac_f32_dpp v48, v124, v40 row_ror:2 row_mask:0xf bank_mask:0xf
	v_fmac_f32_dpp v49, v125, v41 row_ror:2 row_mask:0xf bank_mask:0xf
	v_fmac_f32_dpp v50, v126, v42 row_ror:2 row_mask:0xf bank_mask:0xf
	v_fmac_f32_dpp v51, v127, v43 row_ror:2 row_mask:0xf bank_mask:0xf
	v_pk_mul_f32 v[52:53], v[44:45], v[240:241] op_sel_hi:[1,0]
	v_pk_mul_f32 v[54:55], v[46:47], v[240:241] op_sel_hi:[1,0]
	v_exp_f32_e32 v52, v52
	v_exp_f32_e32 v53, v53
	v_exp_f32_e32 v54, v54
	v_exp_f32_e32 v55, v55
	v_pk_add_f32 v[52:53], v[52:53], v[240:241] op_sel:[0,1] op_sel_hi:[1,1]
	v_pk_add_f32 v[54:55], v[54:55], v[240:241] op_sel:[0,1] op_sel_hi:[1,1]
	v_rcp_f32_e32 v52, v52
	v_rcp_f32_e32 v53, v53
	v_rcp_f32_e32 v54, v54
	v_rcp_f32_e32 v55, v55
	v_pk_mul_f32 v[44:45], v[44:45], v[52:53]
	v_pk_mul_f32 v[46:47], v[46:47], v[54:55]
	v_pk_mul_f32 v[44:45], v[48:49], v[44:45]
	v_pk_mul_f32 v[46:47], v[50:51], v[46:47]
	v_cvt_pk_bf16_f32 v166, v44, v45
	v_cvt_pk_bf16_f32 v167, v46, v47
	v_pk_fma_f32 v[44:45], v[112:113], v[80:81], v[120:121]
	v_pk_fma_f32 v[46:47], v[114:115], v[82:83], v[122:123]
	v_pk_fma_f32 v[48:49], v[108:109], v[76:77], v[116:117]
	v_pk_fma_f32 v[50:51], v[110:111], v[78:79], v[118:119]
	v_fmac_f32_dpp v44, v80, v104 row_shr:1 row_mask:0xf bank_mask:0xf
	v_fmac_f32_dpp v45, v81, v105 row_shr:1 row_mask:0xf bank_mask:0xf
	v_fmac_f32_dpp v46, v82, v106 row_shr:1 row_mask:0xf bank_mask:0xf
	v_fmac_f32_dpp v47, v83, v107 row_shr:1 row_mask:0xf bank_mask:0xf
	v_fmac_f32_dpp v48, v76, v96 row_shr:1 row_mask:0xf bank_mask:0xf
	v_fmac_f32_dpp v49, v77, v97 row_shr:1 row_mask:0xf bank_mask:0xf
	v_fmac_f32_dpp v50, v78, v98 row_shr:1 row_mask:0xf bank_mask:0xf
	v_fmac_f32_dpp v51, v79, v99 row_shr:1 row_mask:0xf bank_mask:0xf
	v_fmac_f32_dpp v44, v80, v100 row_shr:2 row_mask:0xf bank_mask:0xf
	v_fmac_f32_dpp v45, v81, v101 row_shr:2 row_mask:0xf bank_mask:0xf
	v_fmac_f32_dpp v46, v82, v102 row_shr:2 row_mask:0xf bank_mask:0xf
	v_fmac_f32_dpp v47, v83, v103 row_shr:2 row_mask:0xf bank_mask:0xf
	v_fmac_f32_dpp v48, v76, v92 row_shr:2 row_mask:0xf bank_mask:0xf
	v_fmac_f32_dpp v49, v77, v93 row_shr:2 row_mask:0xf bank_mask:0xf
	v_fmac_f32_dpp v50, v78, v94 row_shr:2 row_mask:0xf bank_mask:0xf
	v_fmac_f32_dpp v51, v79, v95 row_shr:2 row_mask:0xf bank_mask:0xf
	v_fmac_f32_dpp v44, v88, v28 row_ror:1 row_mask:0xf bank_mask:0xf
	v_fmac_f32_dpp v45, v89, v29 row_ror:1 row_mask:0xf bank_mask:0xf
	v_fmac_f32_dpp v46, v90, v30 row_ror:1 row_mask:0xf bank_mask:0xf
	v_fmac_f32_dpp v47, v91, v31 row_ror:1 row_mask:0xf bank_mask:0xf
	v_fmac_f32_dpp v48, v84, v36 row_ror:1 row_mask:0xf bank_mask:0xf
	v_fmac_f32_dpp v49, v85, v37 row_ror:1 row_mask:0xf bank_mask:0xf
	v_fmac_f32_dpp v50, v86, v38 row_ror:1 row_mask:0xf bank_mask:0xf
	v_fmac_f32_dpp v51, v87, v39 row_ror:1 row_mask:0xf bank_mask:0xf
	v_fmac_f32_dpp v44, v88, v32 row_ror:2 row_mask:0xf bank_mask:0xf
	v_fmac_f32_dpp v45, v89, v33 row_ror:2 row_mask:0xf bank_mask:0xf
	v_fmac_f32_dpp v46, v90, v34 row_ror:2 row_mask:0xf bank_mask:0xf
	v_fmac_f32_dpp v47, v91, v35 row_ror:2 row_mask:0xf bank_mask:0xf
	v_fmac_f32_dpp v48, v84, v40 row_ror:2 row_mask:0xf bank_mask:0xf
	v_fmac_f32_dpp v49, v85, v41 row_ror:2 row_mask:0xf bank_mask:0xf
	v_fmac_f32_dpp v50, v86, v42 row_ror:2 row_mask:0xf bank_mask:0xf
	v_fmac_f32_dpp v51, v87, v43 row_ror:2 row_mask:0xf bank_mask:0xf
	v_pk_mul_f32 v[52:53], v[44:45], v[240:241] op_sel_hi:[1,0]
	v_pk_mul_f32 v[54:55], v[46:47], v[240:241] op_sel_hi:[1,0]
	v_exp_f32_e32 v52, v52
	v_exp_f32_e32 v53, v53
	v_exp_f32_e32 v54, v54
	v_exp_f32_e32 v55, v55
	v_pk_add_f32 v[52:53], v[52:53], v[240:241] op_sel:[0,1] op_sel_hi:[1,1]
	v_pk_add_f32 v[54:55], v[54:55], v[240:241] op_sel:[0,1] op_sel_hi:[1,1]
	v_rcp_f32_e32 v52, v52
	v_rcp_f32_e32 v53, v53
	v_rcp_f32_e32 v54, v54
	v_rcp_f32_e32 v55, v55
	v_pk_mul_f32 v[44:45], v[44:45], v[52:53]
	v_pk_mul_f32 v[46:47], v[46:47], v[54:55]
	v_pk_mul_f32 v[44:45], v[48:49], v[44:45]
	v_pk_mul_f32 v[46:47], v[50:51], v[46:47]
	v_cvt_pk_bf16_f32 v128, v44, v45
	v_cvt_pk_bf16_f32 v129, v46, v47
	v_pk_fma_f32 v[44:45], v[112:113], v[72:73], v[120:121]
	v_pk_fma_f32 v[46:47], v[114:115], v[74:75], v[122:123]
	v_pk_fma_f32 v[48:49], v[108:109], v[68:69], v[116:117]
	v_pk_fma_f32 v[50:51], v[110:111], v[70:71], v[118:119]
	v_fmac_f32_dpp v44, v72, v104 row_shr:1 row_mask:0xf bank_mask:0xf
	v_fmac_f32_dpp v45, v73, v105 row_shr:1 row_mask:0xf bank_mask:0xf
	v_fmac_f32_dpp v46, v74, v106 row_shr:1 row_mask:0xf bank_mask:0xf
	v_fmac_f32_dpp v47, v75, v107 row_shr:1 row_mask:0xf bank_mask:0xf
	v_fmac_f32_dpp v48, v68, v96 row_shr:1 row_mask:0xf bank_mask:0xf
	v_fmac_f32_dpp v49, v69, v97 row_shr:1 row_mask:0xf bank_mask:0xf
	v_fmac_f32_dpp v50, v70, v98 row_shr:1 row_mask:0xf bank_mask:0xf
	v_fmac_f32_dpp v51, v71, v99 row_shr:1 row_mask:0xf bank_mask:0xf
	v_fmac_f32_dpp v44, v72, v100 row_shr:2 row_mask:0xf bank_mask:0xf
	v_fmac_f32_dpp v45, v73, v101 row_shr:2 row_mask:0xf bank_mask:0xf
	v_fmac_f32_dpp v46, v74, v102 row_shr:2 row_mask:0xf bank_mask:0xf
	v_fmac_f32_dpp v47, v75, v103 row_shr:2 row_mask:0xf bank_mask:0xf
	v_fmac_f32_dpp v48, v68, v92 row_shr:2 row_mask:0xf bank_mask:0xf
	v_fmac_f32_dpp v49, v69, v93 row_shr:2 row_mask:0xf bank_mask:0xf
	v_fmac_f32_dpp v50, v70, v94 row_shr:2 row_mask:0xf bank_mask:0xf
	v_fmac_f32_dpp v51, v71, v95 row_shr:2 row_mask:0xf bank_mask:0xf
	v_fmac_f32_dpp v44, v80, v28 row_ror:1 row_mask:0xf bank_mask:0xf
	v_fmac_f32_dpp v45, v81, v29 row_ror:1 row_mask:0xf bank_mask:0xf
	v_fmac_f32_dpp v46, v82, v30 row_ror:1 row_mask:0xf bank_mask:0xf
	v_fmac_f32_dpp v47, v83, v31 row_ror:1 row_mask:0xf bank_mask:0xf
	v_fmac_f32_dpp v48, v76, v36 row_ror:1 row_mask:0xf bank_mask:0xf
	v_fmac_f32_dpp v49, v77, v37 row_ror:1 row_mask:0xf bank_mask:0xf
	v_fmac_f32_dpp v50, v78, v38 row_ror:1 row_mask:0xf bank_mask:0xf
	v_fmac_f32_dpp v51, v79, v39 row_ror:1 row_mask:0xf bank_mask:0xf
	v_fmac_f32_dpp v44, v80, v32 row_ror:2 row_mask:0xf bank_mask:0xf
	v_fmac_f32_dpp v45, v81, v33 row_ror:2 row_mask:0xf bank_mask:0xf
	v_fmac_f32_dpp v46, v82, v34 row_ror:2 row_mask:0xf bank_mask:0xf
	v_fmac_f32_dpp v47, v83, v35 row_ror:2 row_mask:0xf bank_mask:0xf
	v_fmac_f32_dpp v48, v76, v40 row_ror:2 row_mask:0xf bank_mask:0xf
	v_fmac_f32_dpp v49, v77, v41 row_ror:2 row_mask:0xf bank_mask:0xf
	v_fmac_f32_dpp v50, v78, v42 row_ror:2 row_mask:0xf bank_mask:0xf
	v_fmac_f32_dpp v51, v79, v43 row_ror:2 row_mask:0xf bank_mask:0xf
	v_pk_mul_f32 v[52:53], v[44:45], v[240:241] op_sel_hi:[1,0]
	v_pk_mul_f32 v[54:55], v[46:47], v[240:241] op_sel_hi:[1,0]
	v_exp_f32_e32 v52, v52
	v_exp_f32_e32 v53, v53
	v_exp_f32_e32 v54, v54
	v_exp_f32_e32 v55, v55
	v_pk_add_f32 v[52:53], v[52:53], v[240:241] op_sel:[0,1] op_sel_hi:[1,1]
	v_pk_add_f32 v[54:55], v[54:55], v[240:241] op_sel:[0,1] op_sel_hi:[1,1]
	v_rcp_f32_e32 v52, v52
	v_rcp_f32_e32 v53, v53
	v_rcp_f32_e32 v54, v54
	v_rcp_f32_e32 v55, v55
	v_pk_mul_f32 v[44:45], v[44:45], v[52:53]
	v_pk_mul_f32 v[46:47], v[46:47], v[54:55]
	v_pk_mul_f32 v[44:45], v[48:49], v[44:45]
	v_pk_mul_f32 v[46:47], v[50:51], v[46:47]
	v_cvt_pk_bf16_f32 v130, v44, v45
	v_cvt_pk_bf16_f32 v131, v46, v47
	s_cmp_eq_u32 s63, 0
	s_cbranch_scc1 .Leu_halo_skip_a1n0
	v_subrev_u32_e32 v58, 12, v56
	v_mul_u32_u24_e32 v58, 0xb000, v58
	v_lshl_add_u32 v58, v57, 5, v58
	s_mul_i32 s39, s12, 0x2c000
	s_lshl_b32 s40, s13, 9
	s_add_i32 s39, s39, s40
	s_lshl_b32 s40, s64, 2
	s_add_i32 s39, s39, s40
	s_add_u32 s20, s72, s39
	s_addc_u32 s21, s73, 0
	s_add_u32 s22, s20, 0x5800
	s_addc_u32 s23, s21, 0
	s_and_saveexec_b64 s[8:9], s[10:11]
	global_store_dwordx4 v58, v[72:75], s[20:21]
	global_store_dwordx4 v58, v[68:71], s[22:23]
	s_and_b32 s39, s12, 7
	s_cmp_lg_u32 s39, 7
	s_cbranch_scc1 .Leu_ffn_skip_a1n0
	v_subrev_u32_e32 v59, 14, v56
	v_mul_u32_u24_e32 v59, 0xb000, v59
	v_lshl_add_u32 v59, v57, 5, v59
	s_lshr_b32 s39, s12, 3
	s_mul_i32 s39, s39, 0x16000
	s_lshl_b32 s40, s13, 9
	s_add_i32 s39, s39, s40
	s_lshl_b32 s40, s64, 2
	s_add_i32 s39, s39, s40
	s_add_u32 s20, s28, s39
	s_addc_u32 s21, s29, 0
	s_add_u32 s22, s20, 0x5800
	s_addc_u32 s23, s21, 0
	global_store_dwordx4 v59, v[72:75], s[20:21]
	global_store_dwordx4 v59, v[68:71], s[22:23]

.Leu_pv0_skip_n1:
	s_cmp_eq_u32 s63, 0
	s_movk_i32 s40, 0x1000
	s_cselect_b32 s39, 0x800, s40
	s_add_i32 s39, s39, s67
	v_add_u32_e32 v59, s39, v217
	s_and_saveexec_b64 s[8:9], s[10:11]
	ds_read_b128 v[204:207], v59 offset:16
	ds_read_b128 v[208:211], v59 offset:144
	s_mov_b64 exec, s[8:9]
	s_waitcnt vmcnt(0) lgkmcnt(0)
	v_mul_f32_e32 v28, v192, v250
	v_mul_f32_e32 v29, v193, v250
	v_mul_f32_e32 v30, v194, v250
	v_mul_f32_e32 v31, v195, v250
	v_mul_f32_e32 v32, v236, v251
	v_mul_f32_e32 v33, v237, v251
	v_mul_f32_e32 v34, v238, v251
	v_mul_f32_e32 v35, v239, v251
	v_mul_f32_e32 v36, v176, v250
	v_mul_f32_e32 v37, v177, v250
	v_mul_f32_e32 v38, v178, v250
	v_mul_f32_e32 v39, v179, v250
	v_mul_f32_e32 v40, v184, v251
	v_mul_f32_e32 v41, v185, v251
	v_mul_f32_e32 v42, v186, v251
	v_mul_f32_e32 v43, v187, v251
	v_pk_fma_f32 v[44:45], v[180:181], v[160:161], v[188:189]
	v_pk_fma_f32 v[46:47], v[182:183], v[162:163], v[190:191]
	v_pk_fma_f32 v[48:49], v[172:173], v[156:157], v[168:169]
	v_pk_fma_f32 v[50:51], v[174:175], v[158:159], v[170:171]
	v_fmac_f32_dpp v44, v160, v192 row_shr:1 row_mask:0xf bank_mask:0xf
	v_fmac_f32_dpp v45, v161, v193 row_shr:1 row_mask:0xf bank_mask:0xf
	v_fmac_f32_dpp v46, v162, v194 row_shr:1 row_mask:0xf bank_mask:0xf
	v_fmac_f32_dpp v47, v163, v195 row_shr:1 row_mask:0xf bank_mask:0xf
	v_fmac_f32_dpp v48, v156, v176 row_shr:1 row_mask:0xf bank_mask:0xf
	v_fmac_f32_dpp v49, v157, v177 row_shr:1 row_mask:0xf bank_mask:0xf
	v_fmac_f32_dpp v50, v158, v178 row_shr:1 row_mask:0xf bank_mask:0xf
	v_fmac_f32_dpp v51, v159, v179 row_shr:1 row_mask:0xf bank_mask:0xf
	v_fmac_f32_dpp v44, v160, v236 row_shr:2 row_mask:0xf bank_mask:0xf
	v_fmac_f32_dpp v45, v161, v237 row_shr:2 row_mask:0xf bank_mask:0xf
	v_fmac_f32_dpp v46, v162, v238 row_shr:2 row_mask:0xf bank_mask:0xf
	v_fmac_f32_dpp v47, v163, v239 row_shr:2 row_mask:0xf bank_mask:0xf
	v_fmac_f32_dpp v48, v156, v184 row_shr:2 row_mask:0xf bank_mask:0xf
	v_fmac_f32_dpp v49, v157, v185 row_shr:2 row_mask:0xf bank_mask:0xf
	v_fmac_f32_dpp v50, v158, v186 row_shr:2 row_mask:0xf bank_mask:0xf
	v_fmac_f32_dpp v51, v159, v187 row_shr:2 row_mask:0xf bank_mask:0xf
	v_fmac_f32_dpp v44, v196, v28 row_ror:1 row_mask:0xf bank_mask:0xf
	v_fmac_f32_dpp v45, v197, v29 row_ror:1 row_mask:0xf bank_mask:0xf
	v_fmac_f32_dpp v46, v198, v30 row_ror:1 row_mask:0xf bank_mask:0xf
	v_fmac_f32_dpp v47, v199, v31 row_ror:1 row_mask:0xf bank_mask:0xf
	v_fmac_f32_dpp v48, v200, v36 row_ror:1 row_mask:0xf bank_mask:0xf
	v_fmac_f32_dpp v49, v201, v37 row_ror:1 row_mask:0xf bank_mask:0xf
	v_fmac_f32_dpp v50, v202, v38 row_ror:1 row_mask:0xf bank_mask:0xf
	v_fmac_f32_dpp v51, v203, v39 row_ror:1 row_mask:0xf bank_mask:0xf
	v_fmac_f32_dpp v44, v196, v32 row_ror:2 row_mask:0xf bank_mask:0xf
	v_fmac_f32_dpp v45, v197, v33 row_ror:2 row_mask:0xf bank_mask:0xf
	v_fmac_f32_dpp v46, v198, v34 row_ror:2 row_mask:0xf bank_mask:0xf
	v_fmac_f32_dpp v47, v199, v35 row_ror:2 row_mask:0xf bank_mask:0xf
	v_fmac_f32_dpp v48, v200, v40 row_ror:2 row_mask:0xf bank_mask:0xf
	v_fmac_f32_dpp v49, v201, v41 row_ror:2 row_mask:0xf bank_mask:0xf
	v_fmac_f32_dpp v50, v202, v42 row_ror:2 row_mask:0xf bank_mask:0xf
	v_fmac_f32_dpp v51, v203, v43 row_ror:2 row_mask:0xf bank_mask:0xf
	v_pk_mul_f32 v[52:53], v[44:45], v[240:241] op_sel_hi:[1,0]
	v_pk_mul_f32 v[54:55], v[46:47], v[240:241] op_sel_hi:[1,0]
	v_exp_f32_e32 v52, v52
	v_exp_f32_e32 v53, v53
	v_exp_f32_e32 v54, v54
	v_exp_f32_e32 v55, v55
	v_pk_add_f32 v[52:53], v[52:53], v[240:241] op_sel:[0,1] op_sel_hi:[1,1]
	v_pk_add_f32 v[54:55], v[54:55], v[240:241] op_sel:[0,1] op_sel_hi:[1,1]
	v_rcp_f32_e32 v52, v52
	v_rcp_f32_e32 v53, v53
	v_rcp_f32_e32 v54, v54
	v_rcp_f32_e32 v55, v55
	v_pk_mul_f32 v[44:45], v[44:45], v[52:53]
	v_pk_mul_f32 v[46:47], v[46:47], v[54:55]
	v_pk_mul_f32 v[44:45], v[48:49], v[44:45]
	v_pk_mul_f32 v[46:47], v[50:51], v[46:47]
	v_mov_b32_e32 v124, v242
	v_mov_b32_e32 v125, v243
	v_cvt_pk_bf16_f32 v126, v44, v45
	v_cvt_pk_bf16_f32 v127, v46, v47
	v_mov_b32_e32 v58, v234
	s_mov_b64 s[8:9], exec
	s_and_b32 s39, s12, 7
	s_cmp_eq_u32 s39, 0
	s_cbranch_scc1 .Leu_g00_all
	s_cmp_lg_u32 s63, 0
	s_cbranch_scc1 .Leu_g00_all
	s_andn2_b64 exec, exec, s[14:15]

.Leu_halo_skip_a0n1:
	v_pk_fma_f32 v[44:45], v[180:181], v[152:153], v[188:189]
	v_pk_fma_f32 v[46:47], v[182:183], v[154:155], v[190:191]
	v_pk_fma_f32 v[48:49], v[172:173], v[148:149], v[168:169]
	v_pk_fma_f32 v[50:51], v[174:175], v[150:151], v[170:171]
	v_fmac_f32_dpp v44, v152, v192 row_shr:1 row_mask:0xf bank_mask:0xf
	v_fmac_f32_dpp v45, v153, v193 row_shr:1 row_mask:0xf bank_mask:0xf
	v_fmac_f32_dpp v46, v154, v194 row_shr:1 row_mask:0xf bank_mask:0xf
	v_fmac_f32_dpp v47, v155, v195 row_shr:1 row_mask:0xf bank_mask:0xf
	v_fmac_f32_dpp v48, v148, v176 row_shr:1 row_mask:0xf bank_mask:0xf
	v_fmac_f32_dpp v49, v149, v177 row_shr:1 row_mask:0xf bank_mask:0xf
	v_fmac_f32_dpp v50, v150, v178 row_shr:1 row_mask:0xf bank_mask:0xf
	v_fmac_f32_dpp v51, v151, v179 row_shr:1 row_mask:0xf bank_mask:0xf
	v_fmac_f32_dpp v44, v152, v236 row_shr:2 row_mask:0xf bank_mask:0xf
	v_fmac_f32_dpp v45, v153, v237 row_shr:2 row_mask:0xf bank_mask:0xf
	v_fmac_f32_dpp v46, v154, v238 row_shr:2 row_mask:0xf bank_mask:0xf
	v_fmac_f32_dpp v47, v155, v239 row_shr:2 row_mask:0xf bank_mask:0xf
	v_fmac_f32_dpp v48, v148, v184 row_shr:2 row_mask:0xf bank_mask:0xf
	v_fmac_f32_dpp v49, v149, v185 row_shr:2 row_mask:0xf bank_mask:0xf
	v_fmac_f32_dpp v50, v150, v186 row_shr:2 row_mask:0xf bank_mask:0xf
	v_fmac_f32_dpp v51, v151, v187 row_shr:2 row_mask:0xf bank_mask:0xf
	v_fmac_f32_dpp v44, v160, v28 row_ror:1 row_mask:0xf bank_mask:0xf
	v_fmac_f32_dpp v45, v161, v29 row_ror:1 row_mask:0xf bank_mask:0xf
	v_fmac_f32_dpp v46, v162, v30 row_ror:1 row_mask:0xf bank_mask:0xf
	v_fmac_f32_dpp v47, v163, v31 row_ror:1 row_mask:0xf bank_mask:0xf
	v_fmac_f32_dpp v48, v156, v36 row_ror:1 row_mask:0xf bank_mask:0xf
	v_fmac_f32_dpp v49, v157, v37 row_ror:1 row_mask:0xf bank_mask:0xf
	v_fmac_f32_dpp v50, v158, v38 row_ror:1 row_mask:0xf bank_mask:0xf
	v_fmac_f32_dpp v51, v159, v39 row_ror:1 row_mask:0xf bank_mask:0xf
	v_fmac_f32_dpp v44, v160, v32 row_ror:2 row_mask:0xf bank_mask:0xf
	v_fmac_f32_dpp v45, v161, v33 row_ror:2 row_mask:0xf bank_mask:0xf
	v_fmac_f32_dpp v46, v162, v34 row_ror:2 row_mask:0xf bank_mask:0xf
	v_fmac_f32_dpp v47, v163, v35 row_ror:2 row_mask:0xf bank_mask:0xf
	v_fmac_f32_dpp v48, v156, v40 row_ror:2 row_mask:0xf bank_mask:0xf
	v_fmac_f32_dpp v49, v157, v41 row_ror:2 row_mask:0xf bank_mask:0xf
	v_fmac_f32_dpp v50, v158, v42 row_ror:2 row_mask:0xf bank_mask:0xf
	v_fmac_f32_dpp v51, v159, v43 row_ror:2 row_mask:0xf bank_mask:0xf
	v_pk_mul_f32 v[52:53], v[44:45], v[240:241] op_sel_hi:[1,0]
	v_pk_mul_f32 v[54:55], v[46:47], v[240:241] op_sel_hi:[1,0]
	v_exp_f32_e32 v52, v52
	v_exp_f32_e32 v53, v53
	v_exp_f32_e32 v54, v54
	v_exp_f32_e32 v55, v55
	v_pk_add_f32 v[52:53], v[52:53], v[240:241] op_sel:[0,1] op_sel_hi:[1,1]
	v_pk_add_f32 v[54:55], v[54:55], v[240:241] op_sel:[0,1] op_sel_hi:[1,1]
	v_rcp_f32_e32 v52, v52
	v_rcp_f32_e32 v53, v53
	v_rcp_f32_e32 v54, v54
	v_rcp_f32_e32 v55, v55
	v_pk_mul_f32 v[44:45], v[44:45], v[52:53]
	v_pk_mul_f32 v[46:47], v[46:47], v[54:55]
	v_pk_mul_f32 v[44:45], v[48:49], v[44:45]
	v_pk_mul_f32 v[46:47], v[50:51], v[46:47]
	v_mov_b32_e32 v88, v244
	v_mov_b32_e32 v89, v245
	v_cvt_pk_bf16_f32 v90, v44, v45
	v_cvt_pk_bf16_f32 v91, v46, v47
	v_add_u32_e32 v58, 0x2c000, v234
	global_store_dwordx4 v58, v[88:91], s[16:17]
	v_pk_fma_f32 v[44:45], v[180:181], v[144:145], v[188:189]
	v_pk_fma_f32 v[46:47], v[182:183], v[146:147], v[190:191]
	v_pk_fma_f32 v[48:49], v[172:173], v[140:141], v[168:169]
	v_pk_fma_f32 v[50:51], v[174:175], v[142:143], v[170:171]
	v_fmac_f32_dpp v44, v144, v192 row_shr:1 row_mask:0xf bank_mask:0xf
	v_fmac_f32_dpp v45, v145, v193 row_shr:1 row_mask:0xf bank_mask:0xf
	v_fmac_f32_dpp v46, v146, v194 row_shr:1 row_mask:0xf bank_mask:0xf
	v_fmac_f32_dpp v47, v147, v195 row_shr:1 row_mask:0xf bank_mask:0xf
	v_fmac_f32_dpp v48, v140, v176 row_shr:1 row_mask:0xf bank_mask:0xf
	v_fmac_f32_dpp v49, v141, v177 row_shr:1 row_mask:0xf bank_mask:0xf
	v_fmac_f32_dpp v50, v142, v178 row_shr:1 row_mask:0xf bank_mask:0xf
	v_fmac_f32_dpp v51, v143, v179 row_shr:1 row_mask:0xf bank_mask:0xf
	v_fmac_f32_dpp v44, v144, v236 row_shr:2 row_mask:0xf bank_mask:0xf
	v_fmac_f32_dpp v45, v145, v237 row_shr:2 row_mask:0xf bank_mask:0xf
	v_fmac_f32_dpp v46, v146, v238 row_shr:2 row_mask:0xf bank_mask:0xf
	v_fmac_f32_dpp v47, v147, v239 row_shr:2 row_mask:0xf bank_mask:0xf
	v_fmac_f32_dpp v48, v140, v184 row_shr:2 row_mask:0xf bank_mask:0xf
	v_fmac_f32_dpp v49, v141, v185 row_shr:2 row_mask:0xf bank_mask:0xf
	v_fmac_f32_dpp v50, v142, v186 row_shr:2 row_mask:0xf bank_mask:0xf
	v_fmac_f32_dpp v51, v143, v187 row_shr:2 row_mask:0xf bank_mask:0xf
	v_fmac_f32_dpp v44, v152, v28 row_ror:1 row_mask:0xf bank_mask:0xf
	v_fmac_f32_dpp v45, v153, v29 row_ror:1 row_mask:0xf bank_mask:0xf
	v_fmac_f32_dpp v46, v154, v30 row_ror:1 row_mask:0xf bank_mask:0xf
	v_fmac_f32_dpp v47, v155, v31 row_ror:1 row_mask:0xf bank_mask:0xf
	v_fmac_f32_dpp v48, v148, v36 row_ror:1 row_mask:0xf bank_mask:0xf
	v_fmac_f32_dpp v49, v149, v37 row_ror:1 row_mask:0xf bank_mask:0xf
	v_fmac_f32_dpp v50, v150, v38 row_ror:1 row_mask:0xf bank_mask:0xf
	v_fmac_f32_dpp v51, v151, v39 row_ror:1 row_mask:0xf bank_mask:0xf
	v_fmac_f32_dpp v44, v152, v32 row_ror:2 row_mask:0xf bank_mask:0xf
	v_fmac_f32_dpp v45, v153, v33 row_ror:2 row_mask:0xf bank_mask:0xf
	v_fmac_f32_dpp v46, v154, v34 row_ror:2 row_mask:0xf bank_mask:0xf
	v_fmac_f32_dpp v47, v155, v35 row_ror:2 row_mask:0xf bank_mask:0xf
	v_fmac_f32_dpp v48, v148, v40 row_ror:2 row_mask:0xf bank_mask:0xf
	v_fmac_f32_dpp v49, v149, v41 row_ror:2 row_mask:0xf bank_mask:0xf
	v_fmac_f32_dpp v50, v150, v42 row_ror:2 row_mask:0xf bank_mask:0xf
	v_fmac_f32_dpp v51, v151, v43 row_ror:2 row_mask:0xf bank_mask:0xf
	v_pk_mul_f32 v[52:53], v[44:45], v[240:241] op_sel_hi:[1,0]
	v_pk_mul_f32 v[54:55], v[46:47], v[240:241] op_sel_hi:[1,0]
	v_exp_f32_e32 v52, v52
	v_exp_f32_e32 v53, v53
	v_exp_f32_e32 v54, v54
	v_exp_f32_e32 v55, v55
	v_pk_add_f32 v[52:53], v[52:53], v[240:241] op_sel:[0,1] op_sel_hi:[1,1]
	v_pk_add_f32 v[54:55], v[54:55], v[240:241] op_sel:[0,1] op_sel_hi:[1,1]
	v_rcp_f32_e32 v52, v52
	v_rcp_f32_e32 v53, v53
	v_rcp_f32_e32 v54, v54
	v_rcp_f32_e32 v55, v55
	v_pk_mul_f32 v[44:45], v[44:45], v[52:53]
	v_pk_mul_f32 v[46:47], v[46:47], v[54:55]
	v_pk_mul_f32 v[44:45], v[48:49], v[44:45]
	v_pk_mul_f32 v[46:47], v[50:51], v[46:47]
	v_mov_b32_e32 v124, v246
	v_mov_b32_e32 v125, v247
	v_cvt_pk_bf16_f32 v126, v44, v45
	v_cvt_pk_bf16_f32 v127, v46, v47
	v_add_u32_e32 v58, 0x58000, v234
	global_store_dwordx4 v58, v[124:127], s[16:17]
	v_pk_fma_f32 v[44:45], v[180:181], v[136:137], v[188:189]
	v_pk_fma_f32 v[46:47], v[182:183], v[138:139], v[190:191]
	v_pk_fma_f32 v[48:49], v[172:173], v[132:133], v[168:169]
	v_pk_fma_f32 v[50:51], v[174:175], v[134:135], v[170:171]
	v_fmac_f32_dpp v44, v136, v192 row_shr:1 row_mask:0xf bank_mask:0xf
	v_fmac_f32_dpp v45, v137, v193 row_shr:1 row_mask:0xf bank_mask:0xf
	v_fmac_f32_dpp v46, v138, v194 row_shr:1 row_mask:0xf bank_mask:0xf
	v_fmac_f32_dpp v47, v139, v195 row_shr:1 row_mask:0xf bank_mask:0xf
	v_fmac_f32_dpp v48, v132, v176 row_shr:1 row_mask:0xf bank_mask:0xf
	v_fmac_f32_dpp v49, v133, v177 row_shr:1 row_mask:0xf bank_mask:0xf
	v_fmac_f32_dpp v50, v134, v178 row_shr:1 row_mask:0xf bank_mask:0xf
	v_fmac_f32_dpp v51, v135, v179 row_shr:1 row_mask:0xf bank_mask:0xf
	v_fmac_f32_dpp v44, v136, v236 row_shr:2 row_mask:0xf bank_mask:0xf
	v_fmac_f32_dpp v45, v137, v237 row_shr:2 row_mask:0xf bank_mask:0xf
	v_fmac_f32_dpp v46, v138, v238 row_shr:2 row_mask:0xf bank_mask:0xf
	v_fmac_f32_dpp v47, v139, v239 row_shr:2 row_mask:0xf bank_mask:0xf
	v_fmac_f32_dpp v48, v132, v184 row_shr:2 row_mask:0xf bank_mask:0xf
	v_fmac_f32_dpp v49, v133, v185 row_shr:2 row_mask:0xf bank_mask:0xf
	v_fmac_f32_dpp v50, v134, v186 row_shr:2 row_mask:0xf bank_mask:0xf
	v_fmac_f32_dpp v51, v135, v187 row_shr:2 row_mask:0xf bank_mask:0xf
	v_fmac_f32_dpp v44, v144, v28 row_ror:1 row_mask:0xf bank_mask:0xf
	v_fmac_f32_dpp v45, v145, v29 row_ror:1 row_mask:0xf bank_mask:0xf
	v_fmac_f32_dpp v46, v146, v30 row_ror:1 row_mask:0xf bank_mask:0xf
	v_fmac_f32_dpp v47, v147, v31 row_ror:1 row_mask:0xf bank_mask:0xf
	v_fmac_f32_dpp v48, v140, v36 row_ror:1 row_mask:0xf bank_mask:0xf
	v_fmac_f32_dpp v49, v141, v37 row_ror:1 row_mask:0xf bank_mask:0xf
	v_fmac_f32_dpp v50, v142, v38 row_ror:1 row_mask:0xf bank_mask:0xf
	v_fmac_f32_dpp v51, v143, v39 row_ror:1 row_mask:0xf bank_mask:0xf
	v_fmac_f32_dpp v44, v144, v32 row_ror:2 row_mask:0xf bank_mask:0xf
	v_fmac_f32_dpp v45, v145, v33 row_ror:2 row_mask:0xf bank_mask:0xf
	v_fmac_f32_dpp v46, v146, v34 row_ror:2 row_mask:0xf bank_mask:0xf
	v_fmac_f32_dpp v47, v147, v35 row_ror:2 row_mask:0xf bank_mask:0xf
	v_fmac_f32_dpp v48, v140, v40 row_ror:2 row_mask:0xf bank_mask:0xf
	v_fmac_f32_dpp v49, v141, v41 row_ror:2 row_mask:0xf bank_mask:0xf
	v_fmac_f32_dpp v50, v142, v42 row_ror:2 row_mask:0xf bank_mask:0xf
	v_fmac_f32_dpp v51, v143, v43 row_ror:2 row_mask:0xf bank_mask:0xf
	v_pk_mul_f32 v[52:53], v[44:45], v[240:241] op_sel_hi:[1,0]
	v_pk_mul_f32 v[54:55], v[46:47], v[240:241] op_sel_hi:[1,0]
	v_exp_f32_e32 v52, v52
	v_exp_f32_e32 v53, v53
	v_exp_f32_e32 v54, v54
	v_exp_f32_e32 v55, v55
	v_pk_add_f32 v[52:53], v[52:53], v[240:241] op_sel:[0,1] op_sel_hi:[1,1]
	v_pk_add_f32 v[54:55], v[54:55], v[240:241] op_sel:[0,1] op_sel_hi:[1,1]
	v_rcp_f32_e32 v52, v52
	v_rcp_f32_e32 v53, v53
	v_rcp_f32_e32 v54, v54
	v_rcp_f32_e32 v55, v55
	v_pk_mul_f32 v[44:45], v[44:45], v[52:53]
	v_pk_mul_f32 v[46:47], v[46:47], v[54:55]
	v_pk_mul_f32 v[44:45], v[48:49], v[44:45]
	v_pk_mul_f32 v[46:47], v[50:51], v[46:47]
	v_mov_b32_e32 v88, v248
	v_mov_b32_e32 v89, v249
	v_cvt_pk_bf16_f32 v90, v44, v45
	v_cvt_pk_bf16_f32 v91, v46, v47
	v_add_u32_e32 v58, 0x84000, v234
	global_store_dwordx4 v58, v[88:91], s[16:17]
	v_pk_fma_f32 v[44:45], v[180:181], v[64:65], v[188:189]
	v_pk_fma_f32 v[46:47], v[182:183], v[66:67], v[190:191]
	v_pk_fma_f32 v[48:49], v[172:173], v[60:61], v[168:169]
	v_pk_fma_f32 v[50:51], v[174:175], v[62:63], v[170:171]
	v_fmac_f32_dpp v44, v64, v192 row_shr:1 row_mask:0xf bank_mask:0xf
	v_fmac_f32_dpp v45, v65, v193 row_shr:1 row_mask:0xf bank_mask:0xf
	v_fmac_f32_dpp v46, v66, v194 row_shr:1 row_mask:0xf bank_mask:0xf
	v_fmac_f32_dpp v47, v67, v195 row_shr:1 row_mask:0xf bank_mask:0xf
	v_fmac_f32_dpp v48, v60, v176 row_shr:1 row_mask:0xf bank_mask:0xf
	v_fmac_f32_dpp v49, v61, v177 row_shr:1 row_mask:0xf bank_mask:0xf
	v_fmac_f32_dpp v50, v62, v178 row_shr:1 row_mask:0xf bank_mask:0xf
	v_fmac_f32_dpp v51, v63, v179 row_shr:1 row_mask:0xf bank_mask:0xf
	v_fmac_f32_dpp v44, v64, v236 row_shr:2 row_mask:0xf bank_mask:0xf
	v_fmac_f32_dpp v45, v65, v237 row_shr:2 row_mask:0xf bank_mask:0xf
	v_fmac_f32_dpp v46, v66, v238 row_shr:2 row_mask:0xf bank_mask:0xf
	v_fmac_f32_dpp v47, v67, v239 row_shr:2 row_mask:0xf bank_mask:0xf
	v_fmac_f32_dpp v48, v60, v184 row_shr:2 row_mask:0xf bank_mask:0xf
	v_fmac_f32_dpp v49, v61, v185 row_shr:2 row_mask:0xf bank_mask:0xf
	v_fmac_f32_dpp v50, v62, v186 row_shr:2 row_mask:0xf bank_mask:0xf
	v_fmac_f32_dpp v51, v63, v187 row_shr:2 row_mask:0xf bank_mask:0xf
	v_fmac_f32_dpp v44, v204, v28 row_ror:1 row_mask:0xf bank_mask:0xf
	v_fmac_f32_dpp v45, v205, v29 row_ror:1 row_mask:0xf bank_mask:0xf
	v_fmac_f32_dpp v46, v206, v30 row_ror:1 row_mask:0xf bank_mask:0xf
	v_fmac_f32_dpp v47, v207, v31 row_ror:1 row_mask:0xf bank_mask:0xf
	v_fmac_f32_dpp v48, v208, v36 row_ror:1 row_mask:0xf bank_mask:0xf
	v_fmac_f32_dpp v49, v209, v37 row_ror:1 row_mask:0xf bank_mask:0xf
	v_fmac_f32_dpp v50, v210, v38 row_ror:1 row_mask:0xf bank_mask:0xf
	v_fmac_f32_dpp v51, v211, v39 row_ror:1 row_mask:0xf bank_mask:0xf
	v_fmac_f32_dpp v44, v204, v32 row_ror:2 row_mask:0xf bank_mask:0xf
	v_fmac_f32_dpp v45, v205, v33 row_ror:2 row_mask:0xf bank_mask:0xf
	v_fmac_f32_dpp v46, v206, v34 row_ror:2 row_mask:0xf bank_mask:0xf
	v_fmac_f32_dpp v47, v207, v35 row_ror:2 row_mask:0xf bank_mask:0xf
	v_fmac_f32_dpp v48, v208, v40 row_ror:2 row_mask:0xf bank_mask:0xf
	v_fmac_f32_dpp v49, v209, v41 row_ror:2 row_mask:0xf bank_mask:0xf
	v_fmac_f32_dpp v50, v210, v42 row_ror:2 row_mask:0xf bank_mask:0xf
	v_fmac_f32_dpp v51, v211, v43 row_ror:2 row_mask:0xf bank_mask:0xf
	v_pk_mul_f32 v[52:53], v[44:45], v[240:241] op_sel_hi:[1,0]
	v_pk_mul_f32 v[54:55], v[46:47], v[240:241] op_sel_hi:[1,0]
	v_exp_f32_e32 v52, v52
	v_exp_f32_e32 v53, v53
	v_exp_f32_e32 v54, v54
	v_exp_f32_e32 v55, v55
	v_pk_add_f32 v[52:53], v[52:53], v[240:241] op_sel:[0,1] op_sel_hi:[1,1]
	v_pk_add_f32 v[54:55], v[54:55], v[240:241] op_sel:[0,1] op_sel_hi:[1,1]
	v_rcp_f32_e32 v52, v52
	v_rcp_f32_e32 v53, v53
	v_rcp_f32_e32 v54, v54
	v_rcp_f32_e32 v55, v55
	v_pk_mul_f32 v[44:45], v[44:45], v[52:53]
	v_pk_mul_f32 v[46:47], v[46:47], v[54:55]
	v_pk_mul_f32 v[44:45], v[48:49], v[44:45]
	v_pk_mul_f32 v[46:47], v[50:51], v[46:47]
	v_mov_b32_e32 v124, v164
	v_mov_b32_e32 v125, v165
	v_cvt_pk_bf16_f32 v126, v44, v45
	v_cvt_pk_bf16_f32 v127, v46, v47
	v_mov_b32_e32 v58, v234
	global_store_dwordx4 v58, v[124:127], s[18:19]
	v_pk_fma_f32 v[44:45], v[180:181], v[24:25], v[188:189]
	v_pk_fma_f32 v[46:47], v[182:183], v[26:27], v[190:191]
	v_pk_fma_f32 v[48:49], v[172:173], v[20:21], v[168:169]
	v_pk_fma_f32 v[50:51], v[174:175], v[22:23], v[170:171]
	v_fmac_f32_dpp v44, v24, v192 row_shr:1 row_mask:0xf bank_mask:0xf
	v_fmac_f32_dpp v45, v25, v193 row_shr:1 row_mask:0xf bank_mask:0xf
	v_fmac_f32_dpp v46, v26, v194 row_shr:1 row_mask:0xf bank_mask:0xf
	v_fmac_f32_dpp v47, v27, v195 row_shr:1 row_mask:0xf bank_mask:0xf
	v_fmac_f32_dpp v48, v20, v176 row_shr:1 row_mask:0xf bank_mask:0xf
	v_fmac_f32_dpp v49, v21, v177 row_shr:1 row_mask:0xf bank_mask:0xf
	v_fmac_f32_dpp v50, v22, v178 row_shr:1 row_mask:0xf bank_mask:0xf
	v_fmac_f32_dpp v51, v23, v179 row_shr:1 row_mask:0xf bank_mask:0xf
	v_fmac_f32_dpp v44, v24, v236 row_shr:2 row_mask:0xf bank_mask:0xf
	v_fmac_f32_dpp v45, v25, v237 row_shr:2 row_mask:0xf bank_mask:0xf
	v_fmac_f32_dpp v46, v26, v238 row_shr:2 row_mask:0xf bank_mask:0xf
	v_fmac_f32_dpp v47, v27, v239 row_shr:2 row_mask:0xf bank_mask:0xf
	v_fmac_f32_dpp v48, v20, v184 row_shr:2 row_mask:0xf bank_mask:0xf
	v_fmac_f32_dpp v49, v21, v185 row_shr:2 row_mask:0xf bank_mask:0xf
	v_fmac_f32_dpp v50, v22, v186 row_shr:2 row_mask:0xf bank_mask:0xf
	v_fmac_f32_dpp v51, v23, v187 row_shr:2 row_mask:0xf bank_mask:0xf
	v_fmac_f32_dpp v44, v64, v28 row_ror:1 row_mask:0xf bank_mask:0xf
	v_fmac_f32_dpp v45, v65, v29 row_ror:1 row_mask:0xf bank_mask:0xf
	v_fmac_f32_dpp v46, v66, v30 row_ror:1 row_mask:0xf bank_mask:0xf
	v_fmac_f32_dpp v47, v67, v31 row_ror:1 row_mask:0xf bank_mask:0xf
	v_fmac_f32_dpp v48, v60, v36 row_ror:1 row_mask:0xf bank_mask:0xf
	v_fmac_f32_dpp v49, v61, v37 row_ror:1 row_mask:0xf bank_mask:0xf
	v_fmac_f32_dpp v50, v62, v38 row_ror:1 row_mask:0xf bank_mask:0xf
	v_fmac_f32_dpp v51, v63, v39 row_ror:1 row_mask:0xf bank_mask:0xf
	v_fmac_f32_dpp v44, v64, v32 row_ror:2 row_mask:0xf bank_mask:0xf
	v_fmac_f32_dpp v45, v65, v33 row_ror:2 row_mask:0xf bank_mask:0xf
	v_fmac_f32_dpp v46, v66, v34 row_ror:2 row_mask:0xf bank_mask:0xf
	v_fmac_f32_dpp v47, v67, v35 row_ror:2 row_mask:0xf bank_mask:0xf
	v_fmac_f32_dpp v48, v60, v40 row_ror:2 row_mask:0xf bank_mask:0xf
	v_fmac_f32_dpp v49, v61, v41 row_ror:2 row_mask:0xf bank_mask:0xf
	v_fmac_f32_dpp v50, v62, v42 row_ror:2 row_mask:0xf bank_mask:0xf
	v_fmac_f32_dpp v51, v63, v43 row_ror:2 row_mask:0xf bank_mask:0xf
	v_pk_mul_f32 v[52:53], v[44:45], v[240:241] op_sel_hi:[1,0]
	v_pk_mul_f32 v[54:55], v[46:47], v[240:241] op_sel_hi:[1,0]
	v_exp_f32_e32 v52, v52
	v_exp_f32_e32 v53, v53
	v_exp_f32_e32 v54, v54
	v_exp_f32_e32 v55, v55
	v_pk_add_f32 v[52:53], v[52:53], v[240:241] op_sel:[0,1] op_sel_hi:[1,1]
	v_pk_add_f32 v[54:55], v[54:55], v[240:241] op_sel:[0,1] op_sel_hi:[1,1]
	v_rcp_f32_e32 v52, v52
	v_rcp_f32_e32 v53, v53
	v_rcp_f32_e32 v54, v54
	v_rcp_f32_e32 v55, v55
	v_pk_mul_f32 v[44:45], v[44:45], v[52:53]
	v_pk_mul_f32 v[46:47], v[46:47], v[54:55]
	v_pk_mul_f32 v[44:45], v[48:49], v[44:45]
	v_pk_mul_f32 v[46:47], v[50:51], v[46:47]
	v_mov_b32_e32 v88, v166
	v_mov_b32_e32 v89, v167
	v_cvt_pk_bf16_f32 v90, v44, v45
	v_cvt_pk_bf16_f32 v91, v46, v47
	v_add_u32_e32 v58, 0x2c000, v234
	global_store_dwordx4 v58, v[88:91], s[18:19]
	v_pk_fma_f32 v[44:45], v[180:181], v[16:17], v[188:189]
	v_pk_fma_f32 v[46:47], v[182:183], v[18:19], v[190:191]
	v_pk_fma_f32 v[48:49], v[172:173], v[12:13], v[168:169]
	v_pk_fma_f32 v[50:51], v[174:175], v[14:15], v[170:171]
	v_fmac_f32_dpp v44, v16, v192 row_shr:1 row_mask:0xf bank_mask:0xf
	v_fmac_f32_dpp v45, v17, v193 row_shr:1 row_mask:0xf bank_mask:0xf
	v_fmac_f32_dpp v46, v18, v194 row_shr:1 row_mask:0xf bank_mask:0xf
	v_fmac_f32_dpp v47, v19, v195 row_shr:1 row_mask:0xf bank_mask:0xf
	v_fmac_f32_dpp v48, v12, v176 row_shr:1 row_mask:0xf bank_mask:0xf
	v_fmac_f32_dpp v49, v13, v177 row_shr:1 row_mask:0xf bank_mask:0xf
	v_fmac_f32_dpp v50, v14, v178 row_shr:1 row_mask:0xf bank_mask:0xf
	v_fmac_f32_dpp v51, v15, v179 row_shr:1 row_mask:0xf bank_mask:0xf
	v_fmac_f32_dpp v44, v16, v236 row_shr:2 row_mask:0xf bank_mask:0xf
	v_fmac_f32_dpp v45, v17, v237 row_shr:2 row_mask:0xf bank_mask:0xf
	v_fmac_f32_dpp v46, v18, v238 row_shr:2 row_mask:0xf bank_mask:0xf
	v_fmac_f32_dpp v47, v19, v239 row_shr:2 row_mask:0xf bank_mask:0xf
	v_fmac_f32_dpp v48, v12, v184 row_shr:2 row_mask:0xf bank_mask:0xf
	v_fmac_f32_dpp v49, v13, v185 row_shr:2 row_mask:0xf bank_mask:0xf
	v_fmac_f32_dpp v50, v14, v186 row_shr:2 row_mask:0xf bank_mask:0xf
	v_fmac_f32_dpp v51, v15, v187 row_shr:2 row_mask:0xf bank_mask:0xf
	v_fmac_f32_dpp v44, v24, v28 row_ror:1 row_mask:0xf bank_mask:0xf
	v_fmac_f32_dpp v45, v25, v29 row_ror:1 row_mask:0xf bank_mask:0xf
	v_fmac_f32_dpp v46, v26, v30 row_ror:1 row_mask:0xf bank_mask:0xf
	v_fmac_f32_dpp v47, v27, v31 row_ror:1 row_mask:0xf bank_mask:0xf
	v_fmac_f32_dpp v48, v20, v36 row_ror:1 row_mask:0xf bank_mask:0xf
	v_fmac_f32_dpp v49, v21, v37 row_ror:1 row_mask:0xf bank_mask:0xf
	v_fmac_f32_dpp v50, v22, v38 row_ror:1 row_mask:0xf bank_mask:0xf
	v_fmac_f32_dpp v51, v23, v39 row_ror:1 row_mask:0xf bank_mask:0xf
	v_fmac_f32_dpp v44, v24, v32 row_ror:2 row_mask:0xf bank_mask:0xf
	v_fmac_f32_dpp v45, v25, v33 row_ror:2 row_mask:0xf bank_mask:0xf
	v_fmac_f32_dpp v46, v26, v34 row_ror:2 row_mask:0xf bank_mask:0xf
	v_fmac_f32_dpp v47, v27, v35 row_ror:2 row_mask:0xf bank_mask:0xf
	v_fmac_f32_dpp v48, v20, v40 row_ror:2 row_mask:0xf bank_mask:0xf
	v_fmac_f32_dpp v49, v21, v41 row_ror:2 row_mask:0xf bank_mask:0xf
	v_fmac_f32_dpp v50, v22, v42 row_ror:2 row_mask:0xf bank_mask:0xf
	v_fmac_f32_dpp v51, v23, v43 row_ror:2 row_mask:0xf bank_mask:0xf
	v_pk_mul_f32 v[52:53], v[44:45], v[240:241] op_sel_hi:[1,0]
	v_pk_mul_f32 v[54:55], v[46:47], v[240:241] op_sel_hi:[1,0]
	v_exp_f32_e32 v52, v52
	v_exp_f32_e32 v53, v53
	v_exp_f32_e32 v54, v54
	v_exp_f32_e32 v55, v55
	v_pk_add_f32 v[52:53], v[52:53], v[240:241] op_sel:[0,1] op_sel_hi:[1,1]
	v_pk_add_f32 v[54:55], v[54:55], v[240:241] op_sel:[0,1] op_sel_hi:[1,1]
	v_rcp_f32_e32 v52, v52
	v_rcp_f32_e32 v53, v53
	v_rcp_f32_e32 v54, v54
	v_rcp_f32_e32 v55, v55
	v_pk_mul_f32 v[44:45], v[44:45], v[52:53]
	v_pk_mul_f32 v[46:47], v[46:47], v[54:55]
	v_pk_mul_f32 v[44:45], v[48:49], v[44:45]
	v_pk_mul_f32 v[46:47], v[50:51], v[46:47]
	v_mov_b32_e32 v124, v128
	v_mov_b32_e32 v125, v129
	v_cvt_pk_bf16_f32 v126, v44, v45
	v_cvt_pk_bf16_f32 v127, v46, v47
	v_add_u32_e32 v58, 0x58000, v234
	global_store_dwordx4 v58, v[124:127], s[18:19]
	v_pk_fma_f32 v[44:45], v[180:181], v[8:9], v[188:189]
	v_pk_fma_f32 v[46:47], v[182:183], v[10:11], v[190:191]
	v_pk_fma_f32 v[48:49], v[172:173], v[4:5], v[168:169]
	v_pk_fma_f32 v[50:51], v[174:175], v[6:7], v[170:171]
	v_fmac_f32_dpp v44, v8, v192 row_shr:1 row_mask:0xf bank_mask:0xf
	v_fmac_f32_dpp v45, v9, v193 row_shr:1 row_mask:0xf bank_mask:0xf
	v_fmac_f32_dpp v46, v10, v194 row_shr:1 row_mask:0xf bank_mask:0xf
	v_fmac_f32_dpp v47, v11, v195 row_shr:1 row_mask:0xf bank_mask:0xf
	v_fmac_f32_dpp v48, v4, v176 row_shr:1 row_mask:0xf bank_mask:0xf
	v_fmac_f32_dpp v49, v5, v177 row_shr:1 row_mask:0xf bank_mask:0xf
	v_fmac_f32_dpp v50, v6, v178 row_shr:1 row_mask:0xf bank_mask:0xf
	v_fmac_f32_dpp v51, v7, v179 row_shr:1 row_mask:0xf bank_mask:0xf
	v_fmac_f32_dpp v44, v8, v236 row_shr:2 row_mask:0xf bank_mask:0xf
	v_fmac_f32_dpp v45, v9, v237 row_shr:2 row_mask:0xf bank_mask:0xf
	v_fmac_f32_dpp v46, v10, v238 row_shr:2 row_mask:0xf bank_mask:0xf
	v_fmac_f32_dpp v47, v11, v239 row_shr:2 row_mask:0xf bank_mask:0xf
	v_fmac_f32_dpp v48, v4, v184 row_shr:2 row_mask:0xf bank_mask:0xf
	v_fmac_f32_dpp v49, v5, v185 row_shr:2 row_mask:0xf bank_mask:0xf
	v_fmac_f32_dpp v50, v6, v186 row_shr:2 row_mask:0xf bank_mask:0xf
	v_fmac_f32_dpp v51, v7, v187 row_shr:2 row_mask:0xf bank_mask:0xf
	v_fmac_f32_dpp v44, v16, v28 row_ror:1 row_mask:0xf bank_mask:0xf
	v_fmac_f32_dpp v45, v17, v29 row_ror:1 row_mask:0xf bank_mask:0xf
	v_fmac_f32_dpp v46, v18, v30 row_ror:1 row_mask:0xf bank_mask:0xf
	v_fmac_f32_dpp v47, v19, v31 row_ror:1 row_mask:0xf bank_mask:0xf
	v_fmac_f32_dpp v48, v12, v36 row_ror:1 row_mask:0xf bank_mask:0xf
	v_fmac_f32_dpp v49, v13, v37 row_ror:1 row_mask:0xf bank_mask:0xf
	v_fmac_f32_dpp v50, v14, v38 row_ror:1 row_mask:0xf bank_mask:0xf
	v_fmac_f32_dpp v51, v15, v39 row_ror:1 row_mask:0xf bank_mask:0xf
	v_fmac_f32_dpp v44, v16, v32 row_ror:2 row_mask:0xf bank_mask:0xf
	v_fmac_f32_dpp v45, v17, v33 row_ror:2 row_mask:0xf bank_mask:0xf
	v_fmac_f32_dpp v46, v18, v34 row_ror:2 row_mask:0xf bank_mask:0xf
	v_fmac_f32_dpp v47, v19, v35 row_ror:2 row_mask:0xf bank_mask:0xf
	v_fmac_f32_dpp v48, v12, v40 row_ror:2 row_mask:0xf bank_mask:0xf
	v_fmac_f32_dpp v49, v13, v41 row_ror:2 row_mask:0xf bank_mask:0xf
	v_fmac_f32_dpp v50, v14, v42 row_ror:2 row_mask:0xf bank_mask:0xf
	v_fmac_f32_dpp v51, v15, v43 row_ror:2 row_mask:0xf bank_mask:0xf
	v_pk_mul_f32 v[52:53], v[44:45], v[240:241] op_sel_hi:[1,0]
	v_pk_mul_f32 v[54:55], v[46:47], v[240:241] op_sel_hi:[1,0]
	v_exp_f32_e32 v52, v52
	v_exp_f32_e32 v53, v53
	v_exp_f32_e32 v54, v54
	v_exp_f32_e32 v55, v55
	v_pk_add_f32 v[52:53], v[52:53], v[240:241] op_sel:[0,1] op_sel_hi:[1,1]
	v_pk_add_f32 v[54:55], v[54:55], v[240:241] op_sel:[0,1] op_sel_hi:[1,1]
	v_rcp_f32_e32 v52, v52
	v_rcp_f32_e32 v53, v53
	v_rcp_f32_e32 v54, v54
	v_rcp_f32_e32 v55, v55
	v_pk_mul_f32 v[44:45], v[44:45], v[52:53]
	v_pk_mul_f32 v[46:47], v[46:47], v[54:55]
	v_pk_mul_f32 v[44:45], v[48:49], v[44:45]
	v_pk_mul_f32 v[46:47], v[50:51], v[46:47]
	v_mov_b32_e32 v88, v130
	v_mov_b32_e32 v89, v131
	v_cvt_pk_bf16_f32 v90, v44, v45
	v_cvt_pk_bf16_f32 v91, v46, v47
	v_add_u32_e32 v58, 0x84000, v234
	global_store_dwordx4 v58, v[88:91], s[18:19]
	s_cmp_eq_u32 s63, 0
	s_cbranch_scc1 .Leu_halo_skip_a1n1
	v_subrev_u32_e32 v58, 12, v56
	v_mul_u32_u24_e32 v58, 0xb000, v58
	v_lshl_add_u32 v58, v57, 5, v58
	s_mul_i32 s39, s12, 0x2c000
	s_lshl_b32 s40, s13, 9
	s_add_i32 s39, s39, s40
	s_lshl_b32 s40, s64, 2
	s_add_i32 s39, s39, s40
	s_add_u32 s20, s72, s39
	s_addc_u32 s21, s73, 0
	s_add_u32 s22, s20, 0x5800
	s_addc_u32 s23, s21, 0
	s_and_saveexec_b64 s[8:9], s[10:11]
	global_store_dwordx4 v58, v[8:11], s[20:21] offset:16
	global_store_dwordx4 v58, v[4:7], s[22:23] offset:16
	s_and_b32 s39, s12, 7
	s_cmp_lg_u32 s39, 7
	s_cbranch_scc1 .Leu_ffn_skip_a1n1
	v_subrev_u32_e32 v59, 14, v56
	v_mul_u32_u24_e32 v59, 0xb000, v59
	v_lshl_add_u32 v59, v57, 5, v59
	s_lshr_b32 s39, s12, 3
	s_mul_i32 s39, s39, 0x16000
	s_lshl_b32 s40, s13, 9
	s_add_i32 s39, s39, s40
	s_lshl_b32 s40, s64, 2
	s_add_i32 s39, s39, s40
	s_add_u32 s20, s28, s39
	s_addc_u32 s21, s29, 0
	s_add_u32 s22, s20, 0x5800
	s_addc_u32 s23, s21, 0
	global_store_dwordx4 v59, v[8:11], s[20:21] offset:16
	global_store_dwordx4 v59, v[4:7], s[22:23] offset:16
